# peeled first K-loop iteration of all six GEMM loops with C=0 MFMAs (removes 128 v_mov accumulator zeroing per tile) on top of hand-written SwiGLU epilogue
# speedup vs baseline: 1.0134x; 1.0037x over previous
; #define PG8_STAGE(bufoff, gbase, voff) do { _Pragma("unroll") for (int _i = 0; _i < 2; ++_i) \
;         __builtin_amdgcn_global_load_lds((const unsigned*)((const char*)(gbase) + (voff)[_i]), (PG8_LAS unsigned*)(lds + (bufoff) + ldsw + _i * 8192), 16, 0, 0); } while (0)
; #define PG8_LDA(dst, b, h) do { _Pragma("unroll") for (int m = 0; m < 4; ++m) _Pragma("unroll") for (int k = 0; k < 2; ++k) dst[m][k] = *(const PG8_LAS frag_t*)(lds + PG8_SA(b, h) + aoff + m * 2048 + k * 1024); } while (0)
; #define PG8_LDB(dst, b, h) do { _Pragma("unroll") for (int n = 0; n < 2; ++n) _Pragma("unroll") for (int k = 0; k < 2; ++k) dst[n][k] = *(const PG8_LAS frag_t*)(lds + PG8_SB(b, h) + boff + n * 2048 + k * 1024); } while (0)
; #define PG8_MMA(ai, bj, At, Bt) do { __builtin_amdgcn_s_setprio(1); _Pragma("unroll") for (int m = 0; m < 4; ++m) _Pragma("unroll") for (int n = 0; n < 2; ++n) _Pragma("unroll") for (int k = 0; k < 2; ++k) \
;         acc[ai][bj][m][n] = mma1v<MMAV>(Bt[n][k], At[m][k], acc[ai][bj][m][n]); __builtin_amdgcn_s_setprio(0); } while (0)
; #define PG8_WAIT_V(n) asm volatile("s_waitcnt vmcnt(" #n ")" ::: "memory")
; #define PG8_WAIT_L(n) asm volatile("s_waitcnt lgkmcnt(" #n ")" ::: "memory")
;     ...
;         const bool has_next = S.next(ui + 1, nxt);
;         const char* nA = has_next ? (const char*)g.A + (size_t)nxt.pm * tstep : cA; const char* nB = has_next ? (const char*)g.Bt + (size_t)nxt.pn * tstep : cB;
;         for (int t = 0; t < nt; t += 2) {
;             const bool last = (t == nt - 2);
;             const char* a1 = cA + (size_t)(t + 1) * kstep;
;             const char* a2 = last ? nA : cA + (size_t)(t + 2) * kstep; const char* b2 = last ? nB : cB + (size_t)(t + 2) * kstepB;
;             const char* a3 = a2 + kstep; const char* b3 = b2 + kstepB;
;             if (last && has_next) S.a_ready(nxt);
;             if constexpr (SP2) {
;             PG8_LDB(B0, 0, 0); PG8_LDB(B1, 0, 1); PG8_SCHED; PG8_LDA(At, 0, 0); PG8_STAGE(PG8_SA(1, 1), a1 + hstep, voffA);
;             PG8_WAIT_V(8); PG8_WAIT_L(0); PG8_BAR; PG8_MMA(0, 0, At, B0); PG8_MMA(0, 1, At, B1); PG8_BAR; PG8_SCHED;
;             PG8_LDA(At, 0, 1); PG8_STAGE(PG8_SB(0, 0), b2, voffB); PG8_STAGE(PG8_SB(0, 1), b2 + hstepB, voffB); PG8_STAGE(PG8_SA(0, 0), a2, voffA);
;             PG8_WAIT_V(8); PG8_WAIT_L(0); PG8_BAR; PG8_MMA(1, 0, At, B0); PG8_MMA(1, 1, At, B1); PG8_BAR; PG8_SCHED;
.LBB0_162:
	s_ashr_i32 s15, s14, 31
	s_lshl_b64 s[16:17], s[14:15], 19
	s_add_u32 s16, s0, s16
	s_addc_u32 s17, s1, s17
	s_and_b64 s[18:19], s[4:5], exec
	s_cselect_b32 s15, s17, s25
	s_cselect_b32 s49, s16, s24
	s_ashr_i32 s13, s12, 31
	s_lshl_b64 s[18:19], s[12:13], 19
	s_add_u32 s18, s34, s18
	s_addc_u32 s19, s35, s19
	s_and_b64 s[26:27], s[4:5], exec
	s_cselect_b32 s13, s19, s23
	s_cselect_b32 s50, s18, s22
	s_add_u32 s51, s22, 0x10000
	s_addc_u32 s52, s23, 0
	s_add_u32 s22, s24, 0x40080
	s_addc_u32 s23, s25, 0
	s_mov_b32 s53, -2
	s_add_u32 s24, s22, 0xfffc0080
	s_addc_u32 s25, s23, -1
	s_add_i32 s54, 0, 0x10000
	s_cmp_eq_u32 s53, 12
	s_cselect_b32 s27, s15, s25
	s_cselect_b32 s26, s49, s24
	v_add_u32_e32 v154, s54, v158
	s_cselect_b32 s25, s13, s52
	s_cselect_b32 s24, s50, s51
	s_add_i32 s56, 0, 0x14000
	ds_read_b128 v[142:145], v154
	ds_read_b128 v[146:149], v154 offset:1024
	ds_read_b128 v[150:153], v154 offset:2048
	ds_read_b128 v[174:177], v154 offset:3072
	v_add_u32_e32 v154, s56, v158
	ds_read_b128 v[178:181], v154
	ds_read_b128 v[182:185], v154 offset:1024
	ds_read_b128 v[186:189], v154 offset:2048
	ds_read_b128 v[216:219], v154 offset:3072
	v_lshl_add_u64 v[156:157], s[22:23], 0, v[138:139]
	s_add_i32 m0, s36, 0xc000
	ds_read_b128 v[220:223], v159
	ds_read_b128 v[224:227], v159 offset:1024
	ds_read_b128 v[228:231], v159 offset:2048
	ds_read_b128 v[232:235], v159 offset:3072
	ds_read_b128 v[236:239], v159 offset:4096
	ds_read_b128 v[240:243], v159 offset:5120
	ds_read_b128 v[244:247], v159 offset:6144
	ds_read_b128 v[248:251], v159 offset:7168
	global_load_lds_dwordx4 v[156:157], off
	v_lshl_add_u64 v[156:157], s[22:23], 0, v[140:141]
	s_add_i32 m0, s36, 0xe000
	s_nop 0
	global_load_lds_dwordx4 v[156:157], off
	s_waitcnt vmcnt(8)
	s_waitcnt lgkmcnt(0)
	s_barrier
	s_setprio 1
	s_waitcnt lgkmcnt(0)
	v_mfma_i32_16x16x64_i8 v[126:129], v[142:145], v[220:223], 0
	v_mfma_i32_16x16x64_i8 v[118:121], v[150:153], v[220:223], 0
	v_mfma_i32_16x16x64_i8 v[110:113], v[142:145], v[228:231], 0
	v_mfma_i32_16x16x64_i8 v[102:105], v[150:153], v[228:231], 0
	v_mfma_i32_16x16x64_i8 v[94:97], v[142:145], v[236:239], 0
	v_mfma_i32_16x16x64_i8 v[86:89], v[150:153], v[236:239], 0
	v_mfma_i32_16x16x64_i8 v[78:81], v[142:145], v[244:247], 0
	v_mfma_i32_16x16x64_i8 v[70:73], v[150:153], v[244:247], 0
	v_mfma_i32_16x16x64_i8 v[126:129], v[146:149], v[224:227], v[126:129]
	v_mfma_i32_16x16x64_i8 v[118:121], v[174:177], v[224:227], v[118:121]
	v_mfma_i32_16x16x64_i8 v[110:113], v[146:149], v[232:235], v[110:113]
	v_mfma_i32_16x16x64_i8 v[102:105], v[174:177], v[232:235], v[102:105]
	v_mfma_i32_16x16x64_i8 v[94:97], v[146:149], v[240:243], v[94:97]
	v_mfma_i32_16x16x64_i8 v[86:89], v[174:177], v[240:243], v[86:89]
	v_mfma_i32_16x16x64_i8 v[78:81], v[146:149], v[248:251], v[78:81]
	v_mfma_i32_16x16x64_i8 v[70:73], v[174:177], v[248:251], v[70:73]
	s_setprio 0
	s_setprio 1
	v_mfma_i32_16x16x64_i8 v[122:125], v[178:181], v[220:223], 0
	v_mfma_i32_16x16x64_i8 v[114:117], v[186:189], v[220:223], 0
	v_mfma_i32_16x16x64_i8 v[106:109], v[178:181], v[228:231], 0
	v_mfma_i32_16x16x64_i8 v[98:101], v[186:189], v[228:231], 0
	v_mfma_i32_16x16x64_i8 v[90:93], v[178:181], v[236:239], 0
	v_mfma_i32_16x16x64_i8 v[82:85], v[186:189], v[236:239], 0
	v_mfma_i32_16x16x64_i8 v[74:77], v[178:181], v[244:247], 0
	v_mfma_i32_16x16x64_i8 v[66:69], v[186:189], v[244:247], 0
	v_mfma_i32_16x16x64_i8 v[122:125], v[182:185], v[224:227], v[122:125]
	v_mfma_i32_16x16x64_i8 v[114:117], v[216:219], v[224:227], v[114:117]
	v_mfma_i32_16x16x64_i8 v[106:109], v[182:185], v[232:235], v[106:109]
	v_mfma_i32_16x16x64_i8 v[98:101], v[216:219], v[232:235], v[98:101]
	v_mfma_i32_16x16x64_i8 v[90:93], v[182:185], v[240:243], v[90:93]
	v_mfma_i32_16x16x64_i8 v[82:85], v[216:219], v[240:243], v[82:85]
	v_mfma_i32_16x16x64_i8 v[74:77], v[182:185], v[248:251], v[74:77]
	v_mfma_i32_16x16x64_i8 v[66:69], v[216:219], v[248:251], v[66:69]
	s_setprio 0
	s_barrier
	s_add_i32 s54, s54, s31
	v_lshl_add_u64 v[156:157], s[24:25], 0, v[134:135]
	s_mov_b32 m0, s54
	ds_read_b128 v[220:223], v159 offset:16384
	ds_read_b128 v[224:227], v159 offset:17408
	ds_read_b128 v[228:231], v159 offset:18432
	ds_read_b128 v[232:235], v159 offset:19456
	ds_read_b128 v[236:239], v159 offset:20480
	ds_read_b128 v[240:243], v159 offset:21504
	ds_read_b128 v[244:247], v159 offset:22528
	ds_read_b128 v[248:251], v159 offset:23552
	global_load_lds_dwordx4 v[156:157], off
	s_add_i32 m0, s54, 0x2000
	s_add_u32 s54, s24, 0x4000
	v_lshl_add_u64 v[156:157], s[24:25], 0, v[130:131]
	s_addc_u32 s55, s25, 0
	s_add_i32 s56, s56, s31
	global_load_lds_dwordx4 v[156:157], off
	v_lshl_add_u64 v[156:157], s[54:55], 0, v[134:135]
	s_mov_b32 m0, s56
	v_lshl_add_u64 v[160:161], s[26:27], 0, v[132:133]
	global_load_lds_dwordx4 v[156:157], off
	v_lshl_add_u64 v[156:157], s[54:55], 0, v[130:131]
	s_add_i32 m0, s56, 0x2000
	s_nop 0
	global_load_lds_dwordx4 v[156:157], off
	v_lshl_add_u64 v[156:157], s[26:27], 0, v[136:137]
	s_mov_b32 m0, s36
	s_nop 0
	global_load_lds_dwordx4 v[156:157], off
	s_mov_b32 m0, s37
	s_nop 0
	global_load_lds_dwordx4 v[160:161], off
	s_waitcnt vmcnt(8)
	s_waitcnt lgkmcnt(0)
	s_barrier
; #define PG8_STAGE(bufoff, gbase, voff) do { _Pragma("unroll") for (int _i = 0; _i < 2; ++_i) \
;         __builtin_amdgcn_global_load_lds((const unsigned*)((const char*)(gbase) + (voff)[_i]), (PG8_LAS unsigned*)(lds + (bufoff) + ldsw + _i * 8192), 16, 0, 0); } while (0)
; #define PG8_LDA(dst, b, h) do { _Pragma("unroll") for (int m = 0; m < 4; ++m) _Pragma("unroll") for (int k = 0; k < 2; ++k) dst[m][k] = *(const PG8_LAS frag_t*)(lds + PG8_SA(b, h) + aoff + m * 2048 + k * 1024); } while (0)
; #define PG8_LDB(dst, b, h) do { _Pragma("unroll") for (int n = 0; n < 2; ++n) _Pragma("unroll") for (int k = 0; k < 2; ++k) dst[n][k] = *(const PG8_LAS frag_t*)(lds + PG8_SB(b, h) + boff + n * 2048 + k * 1024); } while (0)
; #define PG8_MMA(ai, bj, At, Bt) do { __builtin_amdgcn_s_setprio(1); _Pragma("unroll") for (int m = 0; m < 4; ++m) _Pragma("unroll") for (int n = 0; n < 2; ++n) _Pragma("unroll") for (int k = 0; k < 2; ++k) \
;         acc[ai][bj][m][n] = mma1v<MMAV>(Bt[n][k], At[m][k], acc[ai][bj][m][n]); __builtin_amdgcn_s_setprio(0); } while (0)
; #define PG8_WAIT_V(n) asm volatile("s_waitcnt vmcnt(" #n ")" ::: "memory")
; #define PG8_WAIT_L(n) asm volatile("s_waitcnt lgkmcnt(" #n ")" ::: "memory")
; #define PG8_BAR __builtin_amdgcn_s_barrier()
; #define PG8_SCHED __builtin_amdgcn_sched_barrier(0)
;     ...
;             PG8_WAIT_V(8); PG8_WAIT_L(0); PG8_BAR; PG8_MMA(0, 0, At, B0); PG8_MMA(0, 1, At, B1); PG8_BAR; PG8_SCHED;
;             PG8_LDA(At, 0, 1); PG8_STAGE(PG8_SB(0, 0), b2, voffB); PG8_STAGE(PG8_SB(0, 1), b2 + hstepB, voffB); PG8_STAGE(PG8_SA(0, 0), a2, voffA);
;             PG8_WAIT_V(8); PG8_WAIT_L(0); PG8_BAR; PG8_MMA(1, 0, At, B0); PG8_MMA(1, 1, At, B1); PG8_BAR; PG8_SCHED;
;             PG8_LDB(B0, 1, 0); PG8_LDB(B1, 1, 1); PG8_SCHED; PG8_LDA(At, 1, 0); PG8_STAGE(PG8_SA(0, 1), a2 + hstep, voffA);
;             PG8_WAIT_V(8); PG8_WAIT_L(0); PG8_BAR; PG8_MMA(0, 0, At, B0); PG8_MMA(0, 1, At, B1); PG8_BAR; PG8_SCHED;
	s_setprio 1
	s_waitcnt lgkmcnt(0)
	v_mfma_i32_16x16x64_i8 v[62:65], v[142:145], v[220:223], 0
	v_mfma_i32_16x16x64_i8 v[54:57], v[150:153], v[220:223], 0
	v_mfma_i32_16x16x64_i8 v[46:49], v[142:145], v[228:231], 0
	v_mfma_i32_16x16x64_i8 v[38:41], v[150:153], v[228:231], 0
	v_mfma_i32_16x16x64_i8 v[30:33], v[142:145], v[236:239], 0
	v_mfma_i32_16x16x64_i8 v[22:25], v[150:153], v[236:239], 0
	v_mfma_i32_16x16x64_i8 v[14:17], v[142:145], v[244:247], 0
	v_mfma_i32_16x16x64_i8 v[6:9], v[150:153], v[244:247], 0
	v_mfma_i32_16x16x64_i8 v[62:65], v[146:149], v[224:227], v[62:65]
	v_mfma_i32_16x16x64_i8 v[54:57], v[174:177], v[224:227], v[54:57]
	v_mfma_i32_16x16x64_i8 v[46:49], v[146:149], v[232:235], v[46:49]
	v_mfma_i32_16x16x64_i8 v[38:41], v[174:177], v[232:235], v[38:41]
	v_mfma_i32_16x16x64_i8 v[30:33], v[146:149], v[240:243], v[30:33]
	v_mfma_i32_16x16x64_i8 v[22:25], v[174:177], v[240:243], v[22:25]
	v_mfma_i32_16x16x64_i8 v[14:17], v[146:149], v[248:251], v[14:17]
	v_mfma_i32_16x16x64_i8 v[6:9], v[174:177], v[248:251], v[6:9]
	s_setprio 0
	s_setprio 1
	v_mfma_i32_16x16x64_i8 v[58:61], v[178:181], v[220:223], 0
	v_mfma_i32_16x16x64_i8 v[50:53], v[186:189], v[220:223], 0
	v_mfma_i32_16x16x64_i8 v[42:45], v[178:181], v[228:231], 0
	v_mfma_i32_16x16x64_i8 v[34:37], v[186:189], v[228:231], 0
	v_mfma_i32_16x16x64_i8 v[26:29], v[178:181], v[236:239], 0
	v_mfma_i32_16x16x64_i8 v[18:21], v[186:189], v[236:239], 0
	v_mfma_i32_16x16x64_i8 v[10:13], v[178:181], v[244:247], 0
	v_mfma_i32_16x16x64_i8 v[2:5], v[186:189], v[244:247], 0
	v_mfma_i32_16x16x64_i8 v[58:61], v[182:185], v[224:227], v[58:61]
	v_mfma_i32_16x16x64_i8 v[50:53], v[216:219], v[224:227], v[50:53]
	v_mfma_i32_16x16x64_i8 v[42:45], v[182:185], v[232:235], v[42:45]
	v_mfma_i32_16x16x64_i8 v[34:37], v[216:219], v[232:235], v[34:37]
	v_mfma_i32_16x16x64_i8 v[26:29], v[182:185], v[240:243], v[26:29]
	v_mfma_i32_16x16x64_i8 v[18:21], v[216:219], v[240:243], v[18:21]
	v_mfma_i32_16x16x64_i8 v[10:13], v[182:185], v[248:251], v[10:13]
	v_mfma_i32_16x16x64_i8 v[2:5], v[216:219], v[248:251], v[2:5]
	s_setprio 0
	s_barrier
	s_add_i32 s54, 0, 0x18000
	v_add_u32_e32 v154, s54, v158
	s_add_i32 s55, 0, 0x1c000
	ds_read_b128 v[142:145], v154
	ds_read_b128 v[146:149], v154 offset:1024
	ds_read_b128 v[150:153], v154 offset:2048
	ds_read_b128 v[174:177], v154 offset:3072
	v_add_u32_e32 v154, s55, v158
	ds_read_b128 v[178:181], v154
	ds_read_b128 v[182:185], v154 offset:1024
	ds_read_b128 v[186:189], v154 offset:2048
	ds_read_b128 v[216:219], v154 offset:3072
	s_add_u32 s26, s26, 0x40000
	s_addc_u32 s27, s27, 0
	s_mov_b32 m0, s38
	v_lshl_add_u64 v[190:191], s[26:27], 0, v[136:137]
	ds_read_b128 v[220:223], v159 offset:32768
	ds_read_b128 v[224:227], v159 offset:33792
	ds_read_b128 v[228:231], v159 offset:34816
	ds_read_b128 v[232:235], v159 offset:35840
	ds_read_b128 v[236:239], v159 offset:36864
	ds_read_b128 v[240:243], v159 offset:37888
	ds_read_b128 v[244:247], v159 offset:38912
	ds_read_b128 v[248:251], v159 offset:39936
	global_load_lds_dwordx4 v[190:191], off
	v_lshl_add_u64 v[190:191], s[26:27], 0, v[132:133]
	s_mov_b32 m0, s39
	s_nop 0
	global_load_lds_dwordx4 v[190:191], off
	s_waitcnt vmcnt(8)
	s_waitcnt lgkmcnt(0)
	s_barrier
	s_setprio 1
	s_waitcnt lgkmcnt(0)
	v_mfma_i32_16x16x64_i8 v[126:129], v[142:145], v[220:223], v[126:129]
	v_mfma_i32_16x16x64_i8 v[118:121], v[150:153], v[220:223], v[118:121]
	v_mfma_i32_16x16x64_i8 v[110:113], v[142:145], v[228:231], v[110:113]
	v_mfma_i32_16x16x64_i8 v[102:105], v[150:153], v[228:231], v[102:105]
	v_mfma_i32_16x16x64_i8 v[94:97], v[142:145], v[236:239], v[94:97]
	v_mfma_i32_16x16x64_i8 v[86:89], v[150:153], v[236:239], v[86:89]
	v_mfma_i32_16x16x64_i8 v[78:81], v[142:145], v[244:247], v[78:81]
	v_mfma_i32_16x16x64_i8 v[70:73], v[150:153], v[244:247], v[70:73]
	v_mfma_i32_16x16x64_i8 v[126:129], v[146:149], v[224:227], v[126:129]
	v_mfma_i32_16x16x64_i8 v[118:121], v[174:177], v[224:227], v[118:121]
	v_mfma_i32_16x16x64_i8 v[110:113], v[146:149], v[232:235], v[110:113]
	v_mfma_i32_16x16x64_i8 v[102:105], v[174:177], v[232:235], v[102:105]
	v_mfma_i32_16x16x64_i8 v[94:97], v[146:149], v[240:243], v[94:97]
	v_mfma_i32_16x16x64_i8 v[86:89], v[174:177], v[240:243], v[86:89]
	v_mfma_i32_16x16x64_i8 v[78:81], v[146:149], v[248:251], v[78:81]
	v_mfma_i32_16x16x64_i8 v[70:73], v[174:177], v[248:251], v[70:73]
	s_setprio 0
	s_setprio 1
	v_mfma_i32_16x16x64_i8 v[122:125], v[178:181], v[220:223], v[122:125]
	v_mfma_i32_16x16x64_i8 v[114:117], v[186:189], v[220:223], v[114:117]
	v_mfma_i32_16x16x64_i8 v[106:109], v[178:181], v[228:231], v[106:109]
	v_mfma_i32_16x16x64_i8 v[98:101], v[186:189], v[228:231], v[98:101]
	v_mfma_i32_16x16x64_i8 v[90:93], v[178:181], v[236:239], v[90:93]
	v_mfma_i32_16x16x64_i8 v[82:85], v[186:189], v[236:239], v[82:85]
	v_mfma_i32_16x16x64_i8 v[74:77], v[178:181], v[244:247], v[74:77]
	v_mfma_i32_16x16x64_i8 v[66:69], v[186:189], v[244:247], v[66:69]
	v_mfma_i32_16x16x64_i8 v[122:125], v[182:185], v[224:227], v[122:125]
	v_mfma_i32_16x16x64_i8 v[114:117], v[216:219], v[224:227], v[114:117]
	v_mfma_i32_16x16x64_i8 v[106:109], v[182:185], v[232:235], v[106:109]
	v_mfma_i32_16x16x64_i8 v[98:101], v[216:219], v[232:235], v[98:101]
	v_mfma_i32_16x16x64_i8 v[90:93], v[182:185], v[240:243], v[90:93]
	v_mfma_i32_16x16x64_i8 v[82:85], v[216:219], v[240:243], v[82:85]
	v_mfma_i32_16x16x64_i8 v[74:77], v[182:185], v[248:251], v[74:77]
	v_mfma_i32_16x16x64_i8 v[66:69], v[216:219], v[248:251], v[66:69]
	s_setprio 0
	s_barrier
; #define PG8_STAGE(bufoff, gbase, voff) do { _Pragma("unroll") for (int _i = 0; _i < 2; ++_i) \
;         __builtin_amdgcn_global_load_lds((const unsigned*)((const char*)(gbase) + (voff)[_i]), (PG8_LAS unsigned*)(lds + (bufoff) + ldsw + _i * 8192), 16, 0, 0); } while (0)
; #define PG8_LDA(dst, b, h) do { _Pragma("unroll") for (int m = 0; m < 4; ++m) _Pragma("unroll") for (int k = 0; k < 2; ++k) dst[m][k] = *(const PG8_LAS frag_t*)(lds + PG8_SA(b, h) + aoff + m * 2048 + k * 1024); } while (0)
; #define PG8_LDB(dst, b, h) do { _Pragma("unroll") for (int n = 0; n < 2; ++n) _Pragma("unroll") for (int k = 0; k < 2; ++k) dst[n][k] = *(const PG8_LAS frag_t*)(lds + PG8_SB(b, h) + boff + n * 2048 + k * 1024); } while (0)
; #define PG8_MMA(ai, bj, At, Bt) do { __builtin_amdgcn_s_setprio(1); _Pragma("unroll") for (int m = 0; m < 4; ++m) _Pragma("unroll") for (int n = 0; n < 2; ++n) _Pragma("unroll") for (int k = 0; k < 2; ++k) \
;         acc[ai][bj][m][n] = mma1v<MMAV>(Bt[n][k], At[m][k], acc[ai][bj][m][n]); __builtin_amdgcn_s_setprio(0); } while (0)
; #define PG8_WAIT_V(n) asm volatile("s_waitcnt vmcnt(" #n ")" ::: "memory")
; #define PG8_WAIT_L(n) asm volatile("s_waitcnt lgkmcnt(" #n ")" ::: "memory")
; #define PG8_BAR __builtin_amdgcn_s_barrier()
; #define PG8_SCHED __builtin_amdgcn_sched_barrier(0)
;     ...
;             PG8_LDB(B0, 1, 0); PG8_LDB(B1, 1, 1); PG8_SCHED; PG8_LDA(At, 1, 0); PG8_STAGE(PG8_SA(0, 1), a2 + hstep, voffA);
;             PG8_WAIT_V(8); PG8_WAIT_L(0); PG8_BAR; PG8_MMA(0, 0, At, B0); PG8_MMA(0, 1, At, B1); PG8_BAR; PG8_SCHED;
;             PG8_LDA(At, 1, 1); PG8_STAGE(PG8_SB(1, 0), b3, voffB); PG8_STAGE(PG8_SB(1, 1), b3 + hstepB, voffB); PG8_STAGE(PG8_SA(1, 0), a3, voffA);
;             PG8_WAIT_V(8); PG8_WAIT_L(0); PG8_BAR; PG8_MMA(1, 0, At, B0); PG8_MMA(1, 1, At, B1); PG8_BAR; PG8_SCHED;
	s_add_u32 s26, s24, 0x8000
	s_addc_u32 s27, s25, 0
	s_add_i32 s54, s54, s31
	v_lshl_add_u64 v[190:191], s[26:27], 0, v[134:135]
	s_mov_b32 m0, s54
	ds_read_b128 v[220:223], v159 offset:49152
	ds_read_b128 v[224:227], v159 offset:50176
	ds_read_b128 v[228:231], v159 offset:51200
	ds_read_b128 v[232:235], v159 offset:52224
	ds_read_b128 v[236:239], v159 offset:53248
	ds_read_b128 v[240:243], v159 offset:54272
	ds_read_b128 v[244:247], v159 offset:55296
	ds_read_b128 v[248:251], v159 offset:56320
	global_load_lds_dwordx4 v[190:191], off
	s_add_i32 m0, s54, 0x2000
	s_add_u32 s24, s24, 0xc000
	v_lshl_add_u64 v[190:191], s[26:27], 0, v[130:131]
	s_addc_u32 s25, s25, 0
	s_add_i32 s26, s55, s31
	global_load_lds_dwordx4 v[190:191], off
	v_lshl_add_u64 v[190:191], s[24:25], 0, v[134:135]
	s_mov_b32 m0, s26
	v_lshl_add_u64 v[156:157], v[156:157], 0, s[78:79]
	global_load_lds_dwordx4 v[190:191], off
	v_lshl_add_u64 v[190:191], s[24:25], 0, v[130:131]
	s_add_i32 m0, s26, 0x2000
	s_nop 0
	global_load_lds_dwordx4 v[190:191], off
	s_mov_b32 m0, s42
	s_nop 0
	global_load_lds_dwordx4 v[156:157], off
	v_lshl_add_u64 v[156:157], v[160:161], 0, s[78:79]
	s_mov_b32 m0, s43
	s_nop 0
	global_load_lds_dwordx4 v[156:157], off
	s_waitcnt vmcnt(8)
	s_waitcnt lgkmcnt(0)
	s_barrier
	s_setprio 1
	s_waitcnt lgkmcnt(0)
	v_mfma_i32_16x16x64_i8 v[62:65], v[142:145], v[220:223], v[62:65]
	v_mfma_i32_16x16x64_i8 v[54:57], v[150:153], v[220:223], v[54:57]
	v_mfma_i32_16x16x64_i8 v[46:49], v[142:145], v[228:231], v[46:49]
	v_mfma_i32_16x16x64_i8 v[38:41], v[150:153], v[228:231], v[38:41]
	v_mfma_i32_16x16x64_i8 v[30:33], v[142:145], v[236:239], v[30:33]
	v_mfma_i32_16x16x64_i8 v[22:25], v[150:153], v[236:239], v[22:25]
	v_mfma_i32_16x16x64_i8 v[14:17], v[142:145], v[244:247], v[14:17]
	v_mfma_i32_16x16x64_i8 v[6:9], v[150:153], v[244:247], v[6:9]
	v_mfma_i32_16x16x64_i8 v[62:65], v[146:149], v[224:227], v[62:65]
	v_mfma_i32_16x16x64_i8 v[54:57], v[174:177], v[224:227], v[54:57]
	v_mfma_i32_16x16x64_i8 v[46:49], v[146:149], v[232:235], v[46:49]
	v_mfma_i32_16x16x64_i8 v[38:41], v[174:177], v[232:235], v[38:41]
	v_mfma_i32_16x16x64_i8 v[30:33], v[146:149], v[240:243], v[30:33]
	v_mfma_i32_16x16x64_i8 v[22:25], v[174:177], v[240:243], v[22:25]
	v_mfma_i32_16x16x64_i8 v[14:17], v[146:149], v[248:251], v[14:17]
	v_mfma_i32_16x16x64_i8 v[6:9], v[174:177], v[248:251], v[6:9]
	s_setprio 0
	s_setprio 1
	v_mfma_i32_16x16x64_i8 v[58:61], v[178:181], v[220:223], v[58:61]
	v_mfma_i32_16x16x64_i8 v[50:53], v[186:189], v[220:223], v[50:53]
	v_mfma_i32_16x16x64_i8 v[42:45], v[178:181], v[228:231], v[42:45]
	v_mfma_i32_16x16x64_i8 v[34:37], v[186:189], v[228:231], v[34:37]
	v_mfma_i32_16x16x64_i8 v[26:29], v[178:181], v[236:239], v[26:29]
	v_mfma_i32_16x16x64_i8 v[18:21], v[186:189], v[236:239], v[18:21]
	v_mfma_i32_16x16x64_i8 v[10:13], v[178:181], v[244:247], v[10:13]
	v_mfma_i32_16x16x64_i8 v[2:5], v[186:189], v[244:247], v[2:5]
	v_mfma_i32_16x16x64_i8 v[58:61], v[182:185], v[224:227], v[58:61]
	v_mfma_i32_16x16x64_i8 v[50:53], v[216:219], v[224:227], v[50:53]
	v_mfma_i32_16x16x64_i8 v[42:45], v[182:185], v[232:235], v[42:45]
	v_mfma_i32_16x16x64_i8 v[34:37], v[216:219], v[232:235], v[34:37]
	v_mfma_i32_16x16x64_i8 v[26:29], v[182:185], v[240:243], v[26:29]
	v_mfma_i32_16x16x64_i8 v[18:21], v[216:219], v[240:243], v[18:21]
	v_mfma_i32_16x16x64_i8 v[10:13], v[182:185], v[248:251], v[10:13]
	v_mfma_i32_16x16x64_i8 v[2:5], v[216:219], v[248:251], v[2:5]
	s_setprio 0
	s_barrier
	s_add_i32 s53, s53, 2
	s_add_u32 s51, s51, 0x10000
	s_addc_u32 s52, s52, 0
	s_add_u32 s22, s22, 0x100
	s_addc_u32 s23, s23, 0

; #define PG8_STAGE(bufoff, gbase, voff) do { _Pragma("unroll") for (int _i = 0; _i < 2; ++_i) \
;         __builtin_amdgcn_global_load_lds((const unsigned*)((const char*)(gbase) + (voff)[_i]), (PG8_LAS unsigned*)(lds + (bufoff) + ldsw + _i * 8192), 16, 0, 0); } while (0)
; #define PG8_LDA(dst, b, h) do { _Pragma("unroll") for (int m = 0; m < 4; ++m) _Pragma("unroll") for (int k = 0; k < 2; ++k) dst[m][k] = *(const PG8_LAS frag_t*)(lds + PG8_SA(b, h) + aoff + m * 2048 + k * 1024); } while (0)
; #define PG8_LDB(dst, b, h) do { _Pragma("unroll") for (int n = 0; n < 2; ++n) _Pragma("unroll") for (int k = 0; k < 2; ++k) dst[n][k] = *(const PG8_LAS frag_t*)(lds + PG8_SB(b, h) + boff + n * 2048 + k * 1024); } while (0)
; #define PG8_MMA(ai, bj, At, Bt) do { __builtin_amdgcn_s_setprio(1); _Pragma("unroll") for (int m = 0; m < 4; ++m) _Pragma("unroll") for (int n = 0; n < 2; ++n) _Pragma("unroll") for (int k = 0; k < 2; ++k) \
;         acc[ai][bj][m][n] = mma1v<MMAV>(Bt[n][k], At[m][k], acc[ai][bj][m][n]); __builtin_amdgcn_s_setprio(0); } while (0)
; #define PG8_WAIT_V(n) asm volatile("s_waitcnt vmcnt(" #n ")" ::: "memory")
; #define PG8_WAIT_L(n) asm volatile("s_waitcnt lgkmcnt(" #n ")" ::: "memory")
;     ...
;         const bool has_next = S.next(ui + 1, nxt);
;         const char* nA = has_next ? (const char*)g.A + (size_t)nxt.pm * tstep : cA; const char* nB = has_next ? (const char*)g.Bt + (size_t)nxt.pn * tstep : cB;
;         for (int t = 0; t < nt; t += 2) {
;             const bool last = (t == nt - 2);
;             const char* a1 = cA + (size_t)(t + 1) * kstep;
;             const char* a2 = last ? nA : cA + (size_t)(t + 2) * kstep; const char* b2 = last ? nB : cB + (size_t)(t + 2) * kstepB;
;             const char* a3 = a2 + kstep; const char* b3 = b2 + kstepB;
;             if (last && has_next) S.a_ready(nxt);
;             if constexpr (SP2) {
;             PG8_LDB(B0, 0, 0); PG8_LDB(B1, 0, 1); PG8_SCHED; PG8_LDA(At, 0, 0); PG8_STAGE(PG8_SA(1, 1), a1 + hstep, voffA);
;             PG8_WAIT_V(8); PG8_WAIT_L(0); PG8_BAR; PG8_MMA(0, 0, At, B0); PG8_MMA(0, 1, At, B1); PG8_BAR; PG8_SCHED;
;             PG8_LDA(At, 0, 1); PG8_STAGE(PG8_SB(0, 0), b2, voffB); PG8_STAGE(PG8_SB(0, 1), b2 + hstepB, voffB); PG8_STAGE(PG8_SA(0, 0), a2, voffA);
;             PG8_WAIT_V(8); PG8_WAIT_L(0); PG8_BAR; PG8_MMA(1, 0, At, B0); PG8_MMA(1, 1, At, B1); PG8_BAR; PG8_SCHED;
.LBB0_247:
	s_add_u32 s6, s24, 0xc000
	s_addc_u32 s7, s25, 0
	s_add_u32 s53, s8, 0x10000
	s_addc_u32 s54, s9, 0
	s_mov_b32 s55, -2
	s_waitcnt lgkmcnt(0)
	s_add_u32 s8, s6, 0x4000
	s_addc_u32 s9, s7, 0
	s_cmpk_eq_i32 s55, 0x54
	s_cselect_b32 s26, s20, s8
	s_cselect_b32 s27, s21, s9
	s_cselect_b32 s24, s22, s53
	s_cselect_b32 s25, s23, s54
	s_add_u32 s8, s26, 0x8000
	s_addc_u32 s9, s27, 0
	s_add_i32 s56, 0, 0x10000
	s_add_i32 s58, 0, 0x14000
	v_add_u32_e32 v142, s56, v216
	v_add_u32_e32 v158, s58, v216
	ds_read_b128 v[130:133], v142
	ds_read_b128 v[134:137], v142 offset:1024
	ds_read_b128 v[138:141], v142 offset:2048
	ds_read_b128 v[142:145], v142 offset:3072
	ds_read_b128 v[146:149], v158
	ds_read_b128 v[150:153], v158 offset:1024
	ds_read_b128 v[154:157], v158 offset:2048
	ds_read_b128 v[158:161], v158 offset:3072
	v_lshl_add_u64 v[242:243], s[6:7], 0, v[180:181]
	s_add_i32 m0, s37, 0xc000
	ds_read_b128 v[184:187], v217
	ds_read_b128 v[188:191], v217 offset:1024
	ds_read_b128 v[218:221], v217 offset:2048
	ds_read_b128 v[222:225], v217 offset:3072
	ds_read_b128 v[226:229], v217 offset:4096
	ds_read_b128 v[230:233], v217 offset:5120
	ds_read_b128 v[234:237], v217 offset:6144
	ds_read_b128 v[238:241], v217 offset:7168
	global_load_lds_dwordx4 v[242:243], off
	v_lshl_add_u64 v[242:243], s[6:7], 0, v[182:183]
	s_add_i32 m0, s37, 0xe000
	s_nop 0
	global_load_lds_dwordx4 v[242:243], off
	s_waitcnt vmcnt(8)
	s_waitcnt lgkmcnt(0)
	s_barrier
	s_setprio 1
	s_waitcnt lgkmcnt(0)
	v_mfma_f32_16x16x32_bf16 v[126:129], v[130:133], v[184:187], 0
	v_mfma_f32_16x16x32_bf16 v[122:125], v[138:141], v[184:187], 0
	v_mfma_f32_16x16x32_bf16 v[110:113], v[130:133], v[218:221], 0
	v_mfma_f32_16x16x32_bf16 v[106:109], v[138:141], v[218:221], 0
	v_mfma_f32_16x16x32_bf16 v[94:97], v[130:133], v[226:229], 0
	v_mfma_f32_16x16x32_bf16 v[90:93], v[138:141], v[226:229], 0
	v_mfma_f32_16x16x32_bf16 v[78:81], v[130:133], v[234:237], 0
	v_mfma_f32_16x16x32_bf16 v[74:77], v[138:141], v[234:237], 0
	v_mfma_f32_16x16x32_bf16 v[126:129], v[134:137], v[188:191], v[126:129]
	v_mfma_f32_16x16x32_bf16 v[122:125], v[142:145], v[188:191], v[122:125]
	v_mfma_f32_16x16x32_bf16 v[110:113], v[134:137], v[222:225], v[110:113]
	v_mfma_f32_16x16x32_bf16 v[106:109], v[142:145], v[222:225], v[106:109]
	v_mfma_f32_16x16x32_bf16 v[94:97], v[134:137], v[230:233], v[94:97]
	v_mfma_f32_16x16x32_bf16 v[90:93], v[142:145], v[230:233], v[90:93]
	v_mfma_f32_16x16x32_bf16 v[78:81], v[134:137], v[238:241], v[78:81]
	v_mfma_f32_16x16x32_bf16 v[74:77], v[142:145], v[238:241], v[74:77]
	s_setprio 0
	s_setprio 1
	v_mfma_f32_16x16x32_bf16 v[118:121], v[146:149], v[184:187], 0
	v_mfma_f32_16x16x32_bf16 v[114:117], v[154:157], v[184:187], 0
	v_mfma_f32_16x16x32_bf16 v[102:105], v[146:149], v[218:221], 0
	v_mfma_f32_16x16x32_bf16 v[98:101], v[154:157], v[218:221], 0
	v_mfma_f32_16x16x32_bf16 v[86:89], v[146:149], v[226:229], 0
	v_mfma_f32_16x16x32_bf16 v[82:85], v[154:157], v[226:229], 0
	v_mfma_f32_16x16x32_bf16 v[70:73], v[146:149], v[234:237], 0
	v_mfma_f32_16x16x32_bf16 v[66:69], v[154:157], v[234:237], 0
	v_mfma_f32_16x16x32_bf16 v[118:121], v[150:153], v[188:191], v[118:121]
	v_mfma_f32_16x16x32_bf16 v[114:117], v[158:161], v[188:191], v[114:117]
	v_mfma_f32_16x16x32_bf16 v[102:105], v[150:153], v[222:225], v[102:105]
	v_mfma_f32_16x16x32_bf16 v[98:101], v[158:161], v[222:225], v[98:101]
	v_mfma_f32_16x16x32_bf16 v[86:89], v[150:153], v[230:233], v[86:89]
	v_mfma_f32_16x16x32_bf16 v[82:85], v[158:161], v[230:233], v[82:85]
	v_mfma_f32_16x16x32_bf16 v[70:73], v[150:153], v[238:241], v[70:73]
	v_mfma_f32_16x16x32_bf16 v[66:69], v[158:161], v[238:241], v[66:69]
	s_setprio 0
	s_barrier
	s_add_i32 s56, s56, s36
	v_lshl_add_u64 v[242:243], s[24:25], 0, v[162:163]
	s_mov_b32 m0, s56
	ds_read_b128 v[184:187], v217 offset:16384
	ds_read_b128 v[188:191], v217 offset:17408
	ds_read_b128 v[218:221], v217 offset:18432
	ds_read_b128 v[222:225], v217 offset:19456
	ds_read_b128 v[226:229], v217 offset:20480
	ds_read_b128 v[230:233], v217 offset:21504
	ds_read_b128 v[234:237], v217 offset:22528
	ds_read_b128 v[238:241], v217 offset:23552
	global_load_lds_dwordx4 v[242:243], off
	s_add_i32 m0, s56, 0x2000
	s_add_u32 s56, s24, 0x4000
	v_lshl_add_u64 v[242:243], s[24:25], 0, v[178:179]
	s_addc_u32 s57, s25, 0
	s_add_i32 s58, s58, s36
	global_load_lds_dwordx4 v[242:243], off
	v_lshl_add_u64 v[242:243], s[56:57], 0, v[162:163]
	s_mov_b32 m0, s58
	s_nop 0
	global_load_lds_dwordx4 v[242:243], off
	v_lshl_add_u64 v[242:243], s[56:57], 0, v[178:179]
	s_add_i32 m0, s58, 0x2000
	s_nop 0
	global_load_lds_dwordx4 v[242:243], off
	v_lshl_add_u64 v[242:243], s[26:27], 0, v[174:175]
	s_mov_b32 m0, s37
	s_nop 0
	global_load_lds_dwordx4 v[242:243], off
	v_lshl_add_u64 v[242:243], s[26:27], 0, v[176:177]
	s_mov_b32 m0, s38
	s_nop 0
	global_load_lds_dwordx4 v[242:243], off
	s_waitcnt vmcnt(8)
	s_waitcnt lgkmcnt(0)
	s_barrier
; #define PG8_STAGE(bufoff, gbase, voff) do { _Pragma("unroll") for (int _i = 0; _i < 2; ++_i) \
;         __builtin_amdgcn_global_load_lds((const unsigned*)((const char*)(gbase) + (voff)[_i]), (PG8_LAS unsigned*)(lds + (bufoff) + ldsw + _i * 8192), 16, 0, 0); } while (0)
; #define PG8_LDA(dst, b, h) do { _Pragma("unroll") for (int m = 0; m < 4; ++m) _Pragma("unroll") for (int k = 0; k < 2; ++k) dst[m][k] = *(const PG8_LAS frag_t*)(lds + PG8_SA(b, h) + aoff + m * 2048 + k * 1024); } while (0)
; #define PG8_LDB(dst, b, h) do { _Pragma("unroll") for (int n = 0; n < 2; ++n) _Pragma("unroll") for (int k = 0; k < 2; ++k) dst[n][k] = *(const PG8_LAS frag_t*)(lds + PG8_SB(b, h) + boff + n * 2048 + k * 1024); } while (0)
; #define PG8_MMA(ai, bj, At, Bt) do { __builtin_amdgcn_s_setprio(1); _Pragma("unroll") for (int m = 0; m < 4; ++m) _Pragma("unroll") for (int n = 0; n < 2; ++n) _Pragma("unroll") for (int k = 0; k < 2; ++k) \
;         acc[ai][bj][m][n] = mma1v<MMAV>(Bt[n][k], At[m][k], acc[ai][bj][m][n]); __builtin_amdgcn_s_setprio(0); } while (0)
; #define PG8_WAIT_V(n) asm volatile("s_waitcnt vmcnt(" #n ")" ::: "memory")
; #define PG8_WAIT_L(n) asm volatile("s_waitcnt lgkmcnt(" #n ")" ::: "memory")
; #define PG8_BAR __builtin_amdgcn_s_barrier()
; #define PG8_SCHED __builtin_amdgcn_sched_barrier(0)
;     ...
;             PG8_WAIT_V(8); PG8_WAIT_L(0); PG8_BAR; PG8_MMA(0, 0, At, B0); PG8_MMA(0, 1, At, B1); PG8_BAR; PG8_SCHED;
;             PG8_LDA(At, 0, 1); PG8_STAGE(PG8_SB(0, 0), b2, voffB); PG8_STAGE(PG8_SB(0, 1), b2 + hstepB, voffB); PG8_STAGE(PG8_SA(0, 0), a2, voffA);
;             PG8_WAIT_V(8); PG8_WAIT_L(0); PG8_BAR; PG8_MMA(1, 0, At, B0); PG8_MMA(1, 1, At, B1); PG8_BAR; PG8_SCHED;
;             PG8_LDB(B0, 1, 0); PG8_LDB(B1, 1, 1); PG8_SCHED; PG8_LDA(At, 1, 0); PG8_STAGE(PG8_SA(0, 1), a2 + hstep, voffA);
;             PG8_WAIT_V(8); PG8_WAIT_L(0); PG8_BAR; PG8_MMA(0, 0, At, B0); PG8_MMA(0, 1, At, B1); PG8_BAR; PG8_SCHED;
	s_setprio 1
	s_waitcnt lgkmcnt(0)
	v_mfma_f32_16x16x32_bf16 v[62:65], v[130:133], v[184:187], 0
	v_mfma_f32_16x16x32_bf16 v[58:61], v[138:141], v[184:187], 0
	v_mfma_f32_16x16x32_bf16 v[46:49], v[130:133], v[218:221], 0
	v_mfma_f32_16x16x32_bf16 v[42:45], v[138:141], v[218:221], 0
	v_mfma_f32_16x16x32_bf16 v[30:33], v[130:133], v[226:229], 0
	v_mfma_f32_16x16x32_bf16 v[26:29], v[138:141], v[226:229], 0
	v_mfma_f32_16x16x32_bf16 v[14:17], v[130:133], v[234:237], 0
	v_mfma_f32_16x16x32_bf16 v[10:13], v[138:141], v[234:237], 0
	v_mfma_f32_16x16x32_bf16 v[62:65], v[134:137], v[188:191], v[62:65]
	v_mfma_f32_16x16x32_bf16 v[58:61], v[142:145], v[188:191], v[58:61]
	v_mfma_f32_16x16x32_bf16 v[46:49], v[134:137], v[222:225], v[46:49]
	v_mfma_f32_16x16x32_bf16 v[42:45], v[142:145], v[222:225], v[42:45]
	v_mfma_f32_16x16x32_bf16 v[30:33], v[134:137], v[230:233], v[30:33]
	v_mfma_f32_16x16x32_bf16 v[26:29], v[142:145], v[230:233], v[26:29]
	v_mfma_f32_16x16x32_bf16 v[14:17], v[134:137], v[238:241], v[14:17]
	v_mfma_f32_16x16x32_bf16 v[10:13], v[142:145], v[238:241], v[10:13]
	s_setprio 0
	s_setprio 1
	v_mfma_f32_16x16x32_bf16 v[54:57], v[146:149], v[184:187], 0
	v_mfma_f32_16x16x32_bf16 v[50:53], v[154:157], v[184:187], 0
	v_mfma_f32_16x16x32_bf16 v[38:41], v[146:149], v[218:221], 0
	v_mfma_f32_16x16x32_bf16 v[34:37], v[154:157], v[218:221], 0
	v_mfma_f32_16x16x32_bf16 v[22:25], v[146:149], v[226:229], 0
	v_mfma_f32_16x16x32_bf16 v[18:21], v[154:157], v[226:229], 0
	v_mfma_f32_16x16x32_bf16 v[6:9], v[146:149], v[234:237], 0
	v_mfma_f32_16x16x32_bf16 v[2:5], v[154:157], v[234:237], 0
	v_mfma_f32_16x16x32_bf16 v[54:57], v[150:153], v[188:191], v[54:57]
	v_mfma_f32_16x16x32_bf16 v[50:53], v[158:161], v[188:191], v[50:53]
	v_mfma_f32_16x16x32_bf16 v[38:41], v[150:153], v[222:225], v[38:41]
	v_mfma_f32_16x16x32_bf16 v[34:37], v[158:161], v[222:225], v[34:37]
	v_mfma_f32_16x16x32_bf16 v[22:25], v[150:153], v[230:233], v[22:25]
	v_mfma_f32_16x16x32_bf16 v[18:21], v[158:161], v[230:233], v[18:21]
	v_mfma_f32_16x16x32_bf16 v[6:9], v[150:153], v[238:241], v[6:9]
	v_mfma_f32_16x16x32_bf16 v[2:5], v[158:161], v[238:241], v[2:5]
	s_setprio 0
	s_barrier
	s_add_i32 s56, 0, 0x18000
	s_add_i32 s57, 0, 0x1c000
	v_add_u32_e32 v142, s56, v216
	v_add_u32_e32 v158, s57, v216
	ds_read_b128 v[130:133], v142
	ds_read_b128 v[134:137], v142 offset:1024
	ds_read_b128 v[138:141], v142 offset:2048
	ds_read_b128 v[142:145], v142 offset:3072
	ds_read_b128 v[146:149], v158
	ds_read_b128 v[150:153], v158 offset:1024
	ds_read_b128 v[154:157], v158 offset:2048
	ds_read_b128 v[158:161], v158 offset:3072
	s_add_u32 s26, s26, 0x4000
	s_addc_u32 s27, s27, 0
	s_mov_b32 m0, s39
	v_lshl_add_u64 v[242:243], s[26:27], 0, v[174:175]
	ds_read_b128 v[184:187], v217 offset:32768
	ds_read_b128 v[188:191], v217 offset:33792
	ds_read_b128 v[218:221], v217 offset:34816
	ds_read_b128 v[222:225], v217 offset:35840
	ds_read_b128 v[226:229], v217 offset:36864
	ds_read_b128 v[230:233], v217 offset:37888
	ds_read_b128 v[234:237], v217 offset:38912
	ds_read_b128 v[238:241], v217 offset:39936
	global_load_lds_dwordx4 v[242:243], off
	v_lshl_add_u64 v[242:243], s[26:27], 0, v[176:177]
	s_mov_b32 m0, s40
	s_nop 0
	global_load_lds_dwordx4 v[242:243], off
	s_waitcnt vmcnt(8)
	s_waitcnt lgkmcnt(0)
	s_barrier
	s_setprio 1
	s_waitcnt lgkmcnt(0)
	v_mfma_f32_16x16x32_bf16 v[126:129], v[130:133], v[184:187], v[126:129]
	v_mfma_f32_16x16x32_bf16 v[122:125], v[138:141], v[184:187], v[122:125]
	v_mfma_f32_16x16x32_bf16 v[110:113], v[130:133], v[218:221], v[110:113]
	v_mfma_f32_16x16x32_bf16 v[106:109], v[138:141], v[218:221], v[106:109]
	v_mfma_f32_16x16x32_bf16 v[94:97], v[130:133], v[226:229], v[94:97]
	v_mfma_f32_16x16x32_bf16 v[90:93], v[138:141], v[226:229], v[90:93]
	v_mfma_f32_16x16x32_bf16 v[78:81], v[130:133], v[234:237], v[78:81]
	v_mfma_f32_16x16x32_bf16 v[74:77], v[138:141], v[234:237], v[74:77]
	v_mfma_f32_16x16x32_bf16 v[126:129], v[134:137], v[188:191], v[126:129]
	v_mfma_f32_16x16x32_bf16 v[122:125], v[142:145], v[188:191], v[122:125]
	v_mfma_f32_16x16x32_bf16 v[110:113], v[134:137], v[222:225], v[110:113]
	v_mfma_f32_16x16x32_bf16 v[106:109], v[142:145], v[222:225], v[106:109]
	v_mfma_f32_16x16x32_bf16 v[94:97], v[134:137], v[230:233], v[94:97]
	v_mfma_f32_16x16x32_bf16 v[90:93], v[142:145], v[230:233], v[90:93]
	v_mfma_f32_16x16x32_bf16 v[78:81], v[134:137], v[238:241], v[78:81]
	v_mfma_f32_16x16x32_bf16 v[74:77], v[142:145], v[238:241], v[74:77]
	s_setprio 0
	s_setprio 1
	v_mfma_f32_16x16x32_bf16 v[118:121], v[146:149], v[184:187], v[118:121]
	v_mfma_f32_16x16x32_bf16 v[114:117], v[154:157], v[184:187], v[114:117]
	v_mfma_f32_16x16x32_bf16 v[102:105], v[146:149], v[218:221], v[102:105]
	v_mfma_f32_16x16x32_bf16 v[98:101], v[154:157], v[218:221], v[98:101]
	v_mfma_f32_16x16x32_bf16 v[86:89], v[146:149], v[226:229], v[86:89]
	v_mfma_f32_16x16x32_bf16 v[82:85], v[154:157], v[226:229], v[82:85]
	v_mfma_f32_16x16x32_bf16 v[70:73], v[146:149], v[234:237], v[70:73]
	v_mfma_f32_16x16x32_bf16 v[66:69], v[154:157], v[234:237], v[66:69]
	v_mfma_f32_16x16x32_bf16 v[118:121], v[150:153], v[188:191], v[118:121]
	v_mfma_f32_16x16x32_bf16 v[114:117], v[158:161], v[188:191], v[114:117]
	v_mfma_f32_16x16x32_bf16 v[102:105], v[150:153], v[222:225], v[102:105]
	v_mfma_f32_16x16x32_bf16 v[98:101], v[158:161], v[222:225], v[98:101]
	v_mfma_f32_16x16x32_bf16 v[86:89], v[150:153], v[230:233], v[86:89]
	v_mfma_f32_16x16x32_bf16 v[82:85], v[158:161], v[230:233], v[82:85]
	v_mfma_f32_16x16x32_bf16 v[70:73], v[150:153], v[238:241], v[70:73]
	v_mfma_f32_16x16x32_bf16 v[66:69], v[158:161], v[238:241], v[66:69]
	s_setprio 0
	s_barrier
; #define PG8_STAGE(bufoff, gbase, voff) do { _Pragma("unroll") for (int _i = 0; _i < 2; ++_i) \
;         __builtin_amdgcn_global_load_lds((const unsigned*)((const char*)(gbase) + (voff)[_i]), (PG8_LAS unsigned*)(lds + (bufoff) + ldsw + _i * 8192), 16, 0, 0); } while (0)
; #define PG8_LDA(dst, b, h) do { _Pragma("unroll") for (int m = 0; m < 4; ++m) _Pragma("unroll") for (int k = 0; k < 2; ++k) dst[m][k] = *(const PG8_LAS frag_t*)(lds + PG8_SA(b, h) + aoff + m * 2048 + k * 1024); } while (0)
; #define PG8_LDB(dst, b, h) do { _Pragma("unroll") for (int n = 0; n < 2; ++n) _Pragma("unroll") for (int k = 0; k < 2; ++k) dst[n][k] = *(const PG8_LAS frag_t*)(lds + PG8_SB(b, h) + boff + n * 2048 + k * 1024); } while (0)
; #define PG8_MMA(ai, bj, At, Bt) do { __builtin_amdgcn_s_setprio(1); _Pragma("unroll") for (int m = 0; m < 4; ++m) _Pragma("unroll") for (int n = 0; n < 2; ++n) _Pragma("unroll") for (int k = 0; k < 2; ++k) \
;         acc[ai][bj][m][n] = mma1v<MMAV>(Bt[n][k], At[m][k], acc[ai][bj][m][n]); __builtin_amdgcn_s_setprio(0); } while (0)
; #define PG8_WAIT_V(n) asm volatile("s_waitcnt vmcnt(" #n ")" ::: "memory")
; #define PG8_WAIT_L(n) asm volatile("s_waitcnt lgkmcnt(" #n ")" ::: "memory")
; #define PG8_BAR __builtin_amdgcn_s_barrier()
; #define PG8_SCHED __builtin_amdgcn_sched_barrier(0)
;     ...
;             PG8_LDB(B0, 1, 0); PG8_LDB(B1, 1, 1); PG8_SCHED; PG8_LDA(At, 1, 0); PG8_STAGE(PG8_SA(0, 1), a2 + hstep, voffA);
;             PG8_WAIT_V(8); PG8_WAIT_L(0); PG8_BAR; PG8_MMA(0, 0, At, B0); PG8_MMA(0, 1, At, B1); PG8_BAR; PG8_SCHED;
;             PG8_LDA(At, 1, 1); PG8_STAGE(PG8_SB(1, 0), b3, voffB); PG8_STAGE(PG8_SB(1, 1), b3 + hstepB, voffB); PG8_STAGE(PG8_SA(1, 0), a3, voffA);
;             PG8_WAIT_V(8); PG8_WAIT_L(0); PG8_BAR; PG8_MMA(1, 0, At, B0); PG8_MMA(1, 1, At, B1); PG8_BAR; PG8_SCHED;
	s_add_u32 s26, s24, 0x8000
	s_addc_u32 s27, s25, 0
	s_add_i32 s56, s56, s36
	v_lshl_add_u64 v[242:243], s[26:27], 0, v[162:163]
	s_mov_b32 m0, s56
	ds_read_b128 v[184:187], v217 offset:49152
	ds_read_b128 v[188:191], v217 offset:50176
	ds_read_b128 v[218:221], v217 offset:51200
	ds_read_b128 v[222:225], v217 offset:52224
	ds_read_b128 v[226:229], v217 offset:53248
	ds_read_b128 v[230:233], v217 offset:54272
	ds_read_b128 v[234:237], v217 offset:55296
	ds_read_b128 v[238:241], v217 offset:56320
	global_load_lds_dwordx4 v[242:243], off
	s_add_i32 m0, s56, 0x2000
	s_add_u32 s24, s24, 0xc000
	v_lshl_add_u64 v[242:243], s[26:27], 0, v[178:179]
	s_addc_u32 s25, s25, 0
	s_add_i32 s26, s57, s36
	global_load_lds_dwordx4 v[242:243], off
	v_lshl_add_u64 v[242:243], s[24:25], 0, v[162:163]
	s_mov_b32 m0, s26
	s_nop 0
	global_load_lds_dwordx4 v[242:243], off
	v_lshl_add_u64 v[242:243], s[24:25], 0, v[178:179]
	s_add_i32 m0, s26, 0x2000
	s_nop 0
	global_load_lds_dwordx4 v[242:243], off
	v_lshl_add_u64 v[242:243], s[8:9], 0, v[174:175]
	s_mov_b32 m0, s44
	s_nop 0
	global_load_lds_dwordx4 v[242:243], off
	v_lshl_add_u64 v[242:243], s[8:9], 0, v[176:177]
	s_mov_b32 m0, s45
	s_nop 0
	global_load_lds_dwordx4 v[242:243], off
	s_waitcnt vmcnt(8)
	s_waitcnt lgkmcnt(0)
	s_barrier
	s_setprio 1
	s_waitcnt lgkmcnt(0)
	v_mfma_f32_16x16x32_bf16 v[62:65], v[130:133], v[184:187], v[62:65]
	v_mfma_f32_16x16x32_bf16 v[58:61], v[138:141], v[184:187], v[58:61]
	v_mfma_f32_16x16x32_bf16 v[46:49], v[130:133], v[218:221], v[46:49]
	v_mfma_f32_16x16x32_bf16 v[42:45], v[138:141], v[218:221], v[42:45]
	v_mfma_f32_16x16x32_bf16 v[30:33], v[130:133], v[226:229], v[30:33]
	v_mfma_f32_16x16x32_bf16 v[26:29], v[138:141], v[226:229], v[26:29]
	v_mfma_f32_16x16x32_bf16 v[14:17], v[130:133], v[234:237], v[14:17]
	v_mfma_f32_16x16x32_bf16 v[10:13], v[138:141], v[234:237], v[10:13]
	v_mfma_f32_16x16x32_bf16 v[62:65], v[134:137], v[188:191], v[62:65]
	v_mfma_f32_16x16x32_bf16 v[58:61], v[142:145], v[188:191], v[58:61]
	v_mfma_f32_16x16x32_bf16 v[46:49], v[134:137], v[222:225], v[46:49]
	v_mfma_f32_16x16x32_bf16 v[42:45], v[142:145], v[222:225], v[42:45]
	v_mfma_f32_16x16x32_bf16 v[30:33], v[134:137], v[230:233], v[30:33]
	v_mfma_f32_16x16x32_bf16 v[26:29], v[142:145], v[230:233], v[26:29]
	v_mfma_f32_16x16x32_bf16 v[14:17], v[134:137], v[238:241], v[14:17]
	v_mfma_f32_16x16x32_bf16 v[10:13], v[142:145], v[238:241], v[10:13]
	s_setprio 0
	s_setprio 1
	v_mfma_f32_16x16x32_bf16 v[54:57], v[146:149], v[184:187], v[54:57]
	v_mfma_f32_16x16x32_bf16 v[50:53], v[154:157], v[184:187], v[50:53]
	v_mfma_f32_16x16x32_bf16 v[38:41], v[146:149], v[218:221], v[38:41]
	v_mfma_f32_16x16x32_bf16 v[34:37], v[154:157], v[218:221], v[34:37]
	v_mfma_f32_16x16x32_bf16 v[22:25], v[146:149], v[226:229], v[22:25]
	v_mfma_f32_16x16x32_bf16 v[18:21], v[154:157], v[226:229], v[18:21]
	v_mfma_f32_16x16x32_bf16 v[6:9], v[146:149], v[234:237], v[6:9]
	v_mfma_f32_16x16x32_bf16 v[2:5], v[154:157], v[234:237], v[2:5]
	v_mfma_f32_16x16x32_bf16 v[54:57], v[150:153], v[188:191], v[54:57]
	v_mfma_f32_16x16x32_bf16 v[50:53], v[158:161], v[188:191], v[50:53]
	v_mfma_f32_16x16x32_bf16 v[38:41], v[150:153], v[222:225], v[38:41]
	v_mfma_f32_16x16x32_bf16 v[34:37], v[158:161], v[222:225], v[34:37]
	v_mfma_f32_16x16x32_bf16 v[22:25], v[150:153], v[230:233], v[22:25]
	v_mfma_f32_16x16x32_bf16 v[18:21], v[158:161], v[230:233], v[18:21]
	v_mfma_f32_16x16x32_bf16 v[6:9], v[150:153], v[238:241], v[6:9]
	v_mfma_f32_16x16x32_bf16 v[2:5], v[158:161], v[238:241], v[2:5]
	s_setprio 0
	s_barrier
	s_add_i32 s55, s55, 2
	s_add_u32 s6, s6, 0x10000
	s_addc_u32 s7, s7, 0
	s_add_u32 s53, s53, 0x10000
	s_addc_u32 s54, s54, 0

; #define PG8_STAGE(bufoff, gbase, voff) do { _Pragma("unroll") for (int _i = 0; _i < 2; ++_i) \
;         __builtin_amdgcn_global_load_lds((const unsigned*)((const char*)(gbase) + (voff)[_i]), (PG8_LAS unsigned*)(lds + (bufoff) + ldsw + _i * 8192), 16, 0, 0); } while (0)
; #define PG8_LDA(dst, b, h) do { _Pragma("unroll") for (int m = 0; m < 4; ++m) _Pragma("unroll") for (int k = 0; k < 2; ++k) dst[m][k] = *(const PG8_LAS frag_t*)(lds + PG8_SA(b, h) + aoff + m * 2048 + k * 1024); } while (0)
; #define PG8_LDB(dst, b, h) do { _Pragma("unroll") for (int n = 0; n < 2; ++n) _Pragma("unroll") for (int k = 0; k < 2; ++k) dst[n][k] = *(const PG8_LAS frag_t*)(lds + PG8_SB(b, h) + boff + n * 2048 + k * 1024); } while (0)
; #define PG8_MMA(ai, bj, At, Bt) do { __builtin_amdgcn_s_setprio(1); _Pragma("unroll") for (int m = 0; m < 4; ++m) _Pragma("unroll") for (int n = 0; n < 2; ++n) _Pragma("unroll") for (int k = 0; k < 2; ++k) \
;         acc[ai][bj][m][n] = mma1v<MMAV>(Bt[n][k], At[m][k], acc[ai][bj][m][n]); __builtin_amdgcn_s_setprio(0); } while (0)
; #define PG8_WAIT_V(n) asm volatile("s_waitcnt vmcnt(" #n ")" ::: "memory")
; #define PG8_WAIT_L(n) asm volatile("s_waitcnt lgkmcnt(" #n ")" ::: "memory")
;     ...
;         const bool has_next = S.next(ui + 1, nxt);
;         const char* nA = has_next ? (const char*)g.A + (size_t)nxt.pm * tstep : cA; const char* nB = has_next ? (const char*)g.Bt + (size_t)nxt.pn * tstep : cB;
;         for (int t = 0; t < nt; t += 2) {
;             const bool last = (t == nt - 2);
;             const char* a1 = cA + (size_t)(t + 1) * kstep;
;             const char* a2 = last ? nA : cA + (size_t)(t + 2) * kstep; const char* b2 = last ? nB : cB + (size_t)(t + 2) * kstepB;
;             const char* a3 = a2 + kstep; const char* b3 = b2 + kstepB;
;             if (last && has_next) S.a_ready(nxt);
;             if constexpr (SP2) {
;             PG8_LDB(B0, 0, 0); PG8_LDB(B1, 0, 1); PG8_SCHED; PG8_LDA(At, 0, 0); PG8_STAGE(PG8_SA(1, 1), a1 + hstep, voffA);
;             PG8_WAIT_V(8); PG8_WAIT_L(0); PG8_BAR; PG8_MMA(0, 0, At, B0); PG8_MMA(0, 1, At, B1); PG8_BAR; PG8_SCHED;
;             PG8_LDA(At, 0, 1); PG8_STAGE(PG8_SB(0, 0), b2, voffB); PG8_STAGE(PG8_SB(0, 1), b2 + hstepB, voffB); PG8_STAGE(PG8_SA(0, 0), a2, voffA);
;             PG8_WAIT_V(8); PG8_WAIT_L(0); PG8_BAR; PG8_MMA(1, 0, At, B0); PG8_MMA(1, 1, At, B1); PG8_BAR; PG8_SCHED;
.LBB0_368:
	s_ashr_i32 s31, s30, 31
	s_lshl_b64 s[10:11], s[30:31], 20
	s_add_u32 s34, s48, s10
	s_addc_u32 s35, s49, s11
	s_and_b64 s[10:11], s[6:7], exec
	s_cselect_b32 s31, s35, s9
	s_cselect_b32 s39, s34, s8
	s_ashr_i32 s29, s28, 31
	s_lshl_b64 s[10:11], s[28:29], 20
	s_add_u32 s36, s50, s10
	s_addc_u32 s37, s51, s11
	s_and_b64 s[10:11], s[6:7], exec
	s_cselect_b32 s29, s37, s1
	s_cselect_b32 s40, s36, s0
	s_add_u32 s41, s0, 0x10000
	s_addc_u32 s42, s1, 0
	s_add_u32 s0, s8, 0x80080
	s_addc_u32 s1, s9, 0
	s_mov_b32 s43, -2
	s_add_u32 s8, s0, 0xfff80080
	s_addc_u32 s9, s1, -1
	s_add_i32 s80, 0, 0x10000
	s_cmp_eq_u32 s43, 28
	s_cselect_b32 s11, s31, s9
	s_cselect_b32 s10, s39, s8
	s_cselect_b32 s9, s29, s42
	s_cselect_b32 s8, s40, s41
	s_add_i32 s82, 0, 0x14000
	v_add_u32_e32 v154, s80, v161
	v_add_u32_e32 v158, s82, v161
	ds_read_b128 v[130:133], v154
	ds_read_b128 v[134:137], v154 offset:1024
	ds_read_b128 v[138:141], v154 offset:2048
	ds_read_b128 v[154:157], v154 offset:3072
	ds_read_b128 v[176:179], v158
	ds_read_b128 v[180:183], v158 offset:1024
	ds_read_b128 v[184:187], v158 offset:2048
	ds_read_b128 v[188:191], v158 offset:3072
	v_lshl_add_u64 v[248:249], s[0:1], 0, v[150:151]
	s_add_i32 m0, s21, 0xc000
	ds_read_b128 v[216:219], v175
	ds_read_b128 v[220:223], v175 offset:1024
	ds_read_b128 v[224:227], v175 offset:2048
	ds_read_b128 v[228:231], v175 offset:3072
	ds_read_b128 v[232:235], v175 offset:4096
	ds_read_b128 v[236:239], v175 offset:5120
	ds_read_b128 v[240:243], v175 offset:6144
	ds_read_b128 v[244:247], v175 offset:7168
	global_load_lds_dwordx4 v[248:249], off
	v_lshl_add_u64 v[248:249], s[0:1], 0, v[152:153]
	s_add_i32 m0, s21, 0xe000
	s_nop 0
	global_load_lds_dwordx4 v[248:249], off
	s_waitcnt vmcnt(8)
	s_waitcnt lgkmcnt(0)
	s_barrier
	s_setprio 1
	s_waitcnt lgkmcnt(0)
	v_mfma_f32_16x16x32_bf16 v[126:129], v[130:133], v[216:219], 0
	v_mfma_f32_16x16x32_bf16 v[122:125], v[138:141], v[216:219], 0
	v_mfma_f32_16x16x32_bf16 v[110:113], v[130:133], v[224:227], 0
	v_mfma_f32_16x16x32_bf16 v[106:109], v[138:141], v[224:227], 0
	v_mfma_f32_16x16x32_bf16 v[94:97], v[130:133], v[232:235], 0
	v_mfma_f32_16x16x32_bf16 v[90:93], v[138:141], v[232:235], 0
	v_mfma_f32_16x16x32_bf16 v[78:81], v[130:133], v[240:243], 0
	v_mfma_f32_16x16x32_bf16 v[74:77], v[138:141], v[240:243], 0
	v_mfma_f32_16x16x32_bf16 v[126:129], v[134:137], v[220:223], v[126:129]
	v_mfma_f32_16x16x32_bf16 v[122:125], v[154:157], v[220:223], v[122:125]
	v_mfma_f32_16x16x32_bf16 v[110:113], v[134:137], v[228:231], v[110:113]
	v_mfma_f32_16x16x32_bf16 v[106:109], v[154:157], v[228:231], v[106:109]
	v_mfma_f32_16x16x32_bf16 v[94:97], v[134:137], v[236:239], v[94:97]
	v_mfma_f32_16x16x32_bf16 v[90:93], v[154:157], v[236:239], v[90:93]
	v_mfma_f32_16x16x32_bf16 v[78:81], v[134:137], v[244:247], v[78:81]
	v_mfma_f32_16x16x32_bf16 v[74:77], v[154:157], v[244:247], v[74:77]
	s_setprio 0
	s_setprio 1
	v_mfma_f32_16x16x32_bf16 v[118:121], v[176:179], v[216:219], 0
	v_mfma_f32_16x16x32_bf16 v[114:117], v[184:187], v[216:219], 0
	v_mfma_f32_16x16x32_bf16 v[102:105], v[176:179], v[224:227], 0
	v_mfma_f32_16x16x32_bf16 v[98:101], v[184:187], v[224:227], 0
	v_mfma_f32_16x16x32_bf16 v[86:89], v[176:179], v[232:235], 0
	v_mfma_f32_16x16x32_bf16 v[82:85], v[184:187], v[232:235], 0
	v_mfma_f32_16x16x32_bf16 v[70:73], v[176:179], v[240:243], 0
	v_mfma_f32_16x16x32_bf16 v[66:69], v[184:187], v[240:243], 0
	v_mfma_f32_16x16x32_bf16 v[118:121], v[180:183], v[220:223], v[118:121]
	v_mfma_f32_16x16x32_bf16 v[114:117], v[188:191], v[220:223], v[114:117]
	v_mfma_f32_16x16x32_bf16 v[102:105], v[180:183], v[228:231], v[102:105]
	v_mfma_f32_16x16x32_bf16 v[98:101], v[188:191], v[228:231], v[98:101]
	v_mfma_f32_16x16x32_bf16 v[86:89], v[180:183], v[236:239], v[86:89]
	v_mfma_f32_16x16x32_bf16 v[82:85], v[188:191], v[236:239], v[82:85]
	v_mfma_f32_16x16x32_bf16 v[70:73], v[180:183], v[244:247], v[70:73]
	v_mfma_f32_16x16x32_bf16 v[66:69], v[188:191], v[244:247], v[66:69]
	s_setprio 0
	s_barrier
	s_add_i32 s80, s80, s53
	v_lshl_add_u64 v[248:249], s[8:9], 0, v[142:143]
	s_mov_b32 m0, s80
	ds_read_b128 v[216:219], v175 offset:16384
	ds_read_b128 v[220:223], v175 offset:17408
	ds_read_b128 v[224:227], v175 offset:18432
	ds_read_b128 v[228:231], v175 offset:19456
	ds_read_b128 v[232:235], v175 offset:20480
	ds_read_b128 v[236:239], v175 offset:21504
	ds_read_b128 v[240:243], v175 offset:22528
	ds_read_b128 v[244:247], v175 offset:23552
	global_load_lds_dwordx4 v[248:249], off
	s_add_i32 m0, s80, 0x2000
	s_add_u32 s80, s8, 0x4000
	v_lshl_add_u64 v[248:249], s[8:9], 0, v[146:147]
	s_addc_u32 s81, s9, 0
	s_add_i32 s82, s82, s53
	global_load_lds_dwordx4 v[248:249], off
	v_lshl_add_u64 v[248:249], s[80:81], 0, v[142:143]
	s_mov_b32 m0, s82
	v_lshl_add_u64 v[250:251], s[10:11], 0, v[144:145]
	global_load_lds_dwordx4 v[248:249], off
	v_lshl_add_u64 v[248:249], s[80:81], 0, v[146:147]
	s_add_i32 m0, s82, 0x2000
	s_nop 0
	global_load_lds_dwordx4 v[248:249], off
	v_lshl_add_u64 v[248:249], s[10:11], 0, v[162:163]
	s_mov_b32 m0, s21
	s_nop 0
	global_load_lds_dwordx4 v[248:249], off
	s_mov_b32 m0, s54
	s_nop 0
	global_load_lds_dwordx4 v[250:251], off
	s_waitcnt vmcnt(8)
	s_waitcnt lgkmcnt(0)
	s_barrier
; #define PG8_STAGE(bufoff, gbase, voff) do { _Pragma("unroll") for (int _i = 0; _i < 2; ++_i) \
;         __builtin_amdgcn_global_load_lds((const unsigned*)((const char*)(gbase) + (voff)[_i]), (PG8_LAS unsigned*)(lds + (bufoff) + ldsw + _i * 8192), 16, 0, 0); } while (0)
; #define PG8_LDA(dst, b, h) do { _Pragma("unroll") for (int m = 0; m < 4; ++m) _Pragma("unroll") for (int k = 0; k < 2; ++k) dst[m][k] = *(const PG8_LAS frag_t*)(lds + PG8_SA(b, h) + aoff + m * 2048 + k * 1024); } while (0)
; #define PG8_LDB(dst, b, h) do { _Pragma("unroll") for (int n = 0; n < 2; ++n) _Pragma("unroll") for (int k = 0; k < 2; ++k) dst[n][k] = *(const PG8_LAS frag_t*)(lds + PG8_SB(b, h) + boff + n * 2048 + k * 1024); } while (0)
; #define PG8_MMA(ai, bj, At, Bt) do { __builtin_amdgcn_s_setprio(1); _Pragma("unroll") for (int m = 0; m < 4; ++m) _Pragma("unroll") for (int n = 0; n < 2; ++n) _Pragma("unroll") for (int k = 0; k < 2; ++k) \
;         acc[ai][bj][m][n] = mma1v<MMAV>(Bt[n][k], At[m][k], acc[ai][bj][m][n]); __builtin_amdgcn_s_setprio(0); } while (0)
; #define PG8_WAIT_V(n) asm volatile("s_waitcnt vmcnt(" #n ")" ::: "memory")
; #define PG8_WAIT_L(n) asm volatile("s_waitcnt lgkmcnt(" #n ")" ::: "memory")
; #define PG8_BAR __builtin_amdgcn_s_barrier()
; #define PG8_SCHED __builtin_amdgcn_sched_barrier(0)
;     ...
;             PG8_WAIT_V(8); PG8_WAIT_L(0); PG8_BAR; PG8_MMA(0, 0, At, B0); PG8_MMA(0, 1, At, B1); PG8_BAR; PG8_SCHED;
;             PG8_LDA(At, 0, 1); PG8_STAGE(PG8_SB(0, 0), b2, voffB); PG8_STAGE(PG8_SB(0, 1), b2 + hstepB, voffB); PG8_STAGE(PG8_SA(0, 0), a2, voffA);
;             PG8_WAIT_V(8); PG8_WAIT_L(0); PG8_BAR; PG8_MMA(1, 0, At, B0); PG8_MMA(1, 1, At, B1); PG8_BAR; PG8_SCHED;
;             PG8_LDB(B0, 1, 0); PG8_LDB(B1, 1, 1); PG8_SCHED; PG8_LDA(At, 1, 0); PG8_STAGE(PG8_SA(0, 1), a2 + hstep, voffA);
;             PG8_WAIT_V(8); PG8_WAIT_L(0); PG8_BAR; PG8_MMA(0, 0, At, B0); PG8_MMA(0, 1, At, B1); PG8_BAR; PG8_SCHED;
	s_setprio 1
	s_waitcnt lgkmcnt(0)
	v_mfma_f32_16x16x32_bf16 v[62:65], v[130:133], v[216:219], 0
	v_mfma_f32_16x16x32_bf16 v[58:61], v[138:141], v[216:219], 0
	v_mfma_f32_16x16x32_bf16 v[46:49], v[130:133], v[224:227], 0
	v_mfma_f32_16x16x32_bf16 v[42:45], v[138:141], v[224:227], 0
	v_mfma_f32_16x16x32_bf16 v[30:33], v[130:133], v[232:235], 0
	v_mfma_f32_16x16x32_bf16 v[26:29], v[138:141], v[232:235], 0
	v_mfma_f32_16x16x32_bf16 v[14:17], v[130:133], v[240:243], 0
	v_mfma_f32_16x16x32_bf16 v[10:13], v[138:141], v[240:243], 0
	v_mfma_f32_16x16x32_bf16 v[62:65], v[134:137], v[220:223], v[62:65]
	v_mfma_f32_16x16x32_bf16 v[58:61], v[154:157], v[220:223], v[58:61]
	v_mfma_f32_16x16x32_bf16 v[46:49], v[134:137], v[228:231], v[46:49]
	v_mfma_f32_16x16x32_bf16 v[42:45], v[154:157], v[228:231], v[42:45]
	v_mfma_f32_16x16x32_bf16 v[30:33], v[134:137], v[236:239], v[30:33]
	v_mfma_f32_16x16x32_bf16 v[26:29], v[154:157], v[236:239], v[26:29]
	v_mfma_f32_16x16x32_bf16 v[14:17], v[134:137], v[244:247], v[14:17]
	v_mfma_f32_16x16x32_bf16 v[10:13], v[154:157], v[244:247], v[10:13]
	s_setprio 0
	s_setprio 1
	v_mfma_f32_16x16x32_bf16 v[54:57], v[176:179], v[216:219], 0
	v_mfma_f32_16x16x32_bf16 v[50:53], v[184:187], v[216:219], 0
	v_mfma_f32_16x16x32_bf16 v[38:41], v[176:179], v[224:227], 0
	v_mfma_f32_16x16x32_bf16 v[34:37], v[184:187], v[224:227], 0
	v_mfma_f32_16x16x32_bf16 v[22:25], v[176:179], v[232:235], 0
	v_mfma_f32_16x16x32_bf16 v[18:21], v[184:187], v[232:235], 0
	v_mfma_f32_16x16x32_bf16 v[6:9], v[176:179], v[240:243], 0
	v_mfma_f32_16x16x32_bf16 v[2:5], v[184:187], v[240:243], 0
	v_mfma_f32_16x16x32_bf16 v[54:57], v[180:183], v[220:223], v[54:57]
	v_mfma_f32_16x16x32_bf16 v[50:53], v[188:191], v[220:223], v[50:53]
	v_mfma_f32_16x16x32_bf16 v[38:41], v[180:183], v[228:231], v[38:41]
	v_mfma_f32_16x16x32_bf16 v[34:37], v[188:191], v[228:231], v[34:37]
	v_mfma_f32_16x16x32_bf16 v[22:25], v[180:183], v[236:239], v[22:25]
	v_mfma_f32_16x16x32_bf16 v[18:21], v[188:191], v[236:239], v[18:21]
	v_mfma_f32_16x16x32_bf16 v[6:9], v[180:183], v[244:247], v[6:9]
	v_mfma_f32_16x16x32_bf16 v[2:5], v[188:191], v[244:247], v[2:5]
	s_setprio 0
	s_barrier
	s_add_i32 s80, 0, 0x18000
	s_add_i32 s81, 0, 0x1c000
	v_add_u32_e32 v154, s80, v161
	v_add_u32_e32 v158, s81, v161
	ds_read_b128 v[130:133], v154
	ds_read_b128 v[134:137], v154 offset:1024
	ds_read_b128 v[138:141], v154 offset:2048
	ds_read_b128 v[154:157], v154 offset:3072
	ds_read_b128 v[176:179], v158
	ds_read_b128 v[180:183], v158 offset:1024
	ds_read_b128 v[184:187], v158 offset:2048
	ds_read_b128 v[188:191], v158 offset:3072
	s_add_u32 s10, s10, 0x80000
	s_addc_u32 s11, s11, 0
	s_mov_b32 m0, s55
	v_lshl_add_u64 v[252:253], s[10:11], 0, v[162:163]
	ds_read_b128 v[216:219], v175 offset:32768
	ds_read_b128 v[220:223], v175 offset:33792
	ds_read_b128 v[224:227], v175 offset:34816
	ds_read_b128 v[228:231], v175 offset:35840
	ds_read_b128 v[232:235], v175 offset:36864
	ds_read_b128 v[236:239], v175 offset:37888
	ds_read_b128 v[240:243], v175 offset:38912
	ds_read_b128 v[244:247], v175 offset:39936
	global_load_lds_dwordx4 v[252:253], off
	v_lshl_add_u64 v[252:253], s[10:11], 0, v[144:145]
	s_mov_b32 m0, s56
	s_nop 0
	global_load_lds_dwordx4 v[252:253], off
	s_waitcnt vmcnt(8)
	s_waitcnt lgkmcnt(0)
	s_barrier
	s_setprio 1
	s_waitcnt lgkmcnt(0)
	v_mfma_f32_16x16x32_bf16 v[126:129], v[130:133], v[216:219], v[126:129]
	v_mfma_f32_16x16x32_bf16 v[122:125], v[138:141], v[216:219], v[122:125]
	v_mfma_f32_16x16x32_bf16 v[110:113], v[130:133], v[224:227], v[110:113]
	v_mfma_f32_16x16x32_bf16 v[106:109], v[138:141], v[224:227], v[106:109]
	v_mfma_f32_16x16x32_bf16 v[94:97], v[130:133], v[232:235], v[94:97]
	v_mfma_f32_16x16x32_bf16 v[90:93], v[138:141], v[232:235], v[90:93]
	v_mfma_f32_16x16x32_bf16 v[78:81], v[130:133], v[240:243], v[78:81]
	v_mfma_f32_16x16x32_bf16 v[74:77], v[138:141], v[240:243], v[74:77]
	v_mfma_f32_16x16x32_bf16 v[126:129], v[134:137], v[220:223], v[126:129]
	v_mfma_f32_16x16x32_bf16 v[122:125], v[154:157], v[220:223], v[122:125]
	v_mfma_f32_16x16x32_bf16 v[110:113], v[134:137], v[228:231], v[110:113]
	v_mfma_f32_16x16x32_bf16 v[106:109], v[154:157], v[228:231], v[106:109]
	v_mfma_f32_16x16x32_bf16 v[94:97], v[134:137], v[236:239], v[94:97]
	v_mfma_f32_16x16x32_bf16 v[90:93], v[154:157], v[236:239], v[90:93]
	v_mfma_f32_16x16x32_bf16 v[78:81], v[134:137], v[244:247], v[78:81]
	v_mfma_f32_16x16x32_bf16 v[74:77], v[154:157], v[244:247], v[74:77]
	s_setprio 0
	s_setprio 1
	v_mfma_f32_16x16x32_bf16 v[118:121], v[176:179], v[216:219], v[118:121]
	v_mfma_f32_16x16x32_bf16 v[114:117], v[184:187], v[216:219], v[114:117]
	v_mfma_f32_16x16x32_bf16 v[102:105], v[176:179], v[224:227], v[102:105]
	v_mfma_f32_16x16x32_bf16 v[98:101], v[184:187], v[224:227], v[98:101]
	v_mfma_f32_16x16x32_bf16 v[86:89], v[176:179], v[232:235], v[86:89]
	v_mfma_f32_16x16x32_bf16 v[82:85], v[184:187], v[232:235], v[82:85]
	v_mfma_f32_16x16x32_bf16 v[70:73], v[176:179], v[240:243], v[70:73]
	v_mfma_f32_16x16x32_bf16 v[66:69], v[184:187], v[240:243], v[66:69]
	v_mfma_f32_16x16x32_bf16 v[118:121], v[180:183], v[220:223], v[118:121]
	v_mfma_f32_16x16x32_bf16 v[114:117], v[188:191], v[220:223], v[114:117]
	v_mfma_f32_16x16x32_bf16 v[102:105], v[180:183], v[228:231], v[102:105]
	v_mfma_f32_16x16x32_bf16 v[98:101], v[188:191], v[228:231], v[98:101]
	v_mfma_f32_16x16x32_bf16 v[86:89], v[180:183], v[236:239], v[86:89]
	v_mfma_f32_16x16x32_bf16 v[82:85], v[188:191], v[236:239], v[82:85]
	v_mfma_f32_16x16x32_bf16 v[70:73], v[180:183], v[244:247], v[70:73]
	v_mfma_f32_16x16x32_bf16 v[66:69], v[188:191], v[244:247], v[66:69]
	s_setprio 0
	s_barrier
; #define PG8_STAGE(bufoff, gbase, voff) do { _Pragma("unroll") for (int _i = 0; _i < 2; ++_i) \
;         __builtin_amdgcn_global_load_lds((const unsigned*)((const char*)(gbase) + (voff)[_i]), (PG8_LAS unsigned*)(lds + (bufoff) + ldsw + _i * 8192), 16, 0, 0); } while (0)
; #define PG8_LDA(dst, b, h) do { _Pragma("unroll") for (int m = 0; m < 4; ++m) _Pragma("unroll") for (int k = 0; k < 2; ++k) dst[m][k] = *(const PG8_LAS frag_t*)(lds + PG8_SA(b, h) + aoff + m * 2048 + k * 1024); } while (0)
; #define PG8_LDB(dst, b, h) do { _Pragma("unroll") for (int n = 0; n < 2; ++n) _Pragma("unroll") for (int k = 0; k < 2; ++k) dst[n][k] = *(const PG8_LAS frag_t*)(lds + PG8_SB(b, h) + boff + n * 2048 + k * 1024); } while (0)
; #define PG8_MMA(ai, bj, At, Bt) do { __builtin_amdgcn_s_setprio(1); _Pragma("unroll") for (int m = 0; m < 4; ++m) _Pragma("unroll") for (int n = 0; n < 2; ++n) _Pragma("unroll") for (int k = 0; k < 2; ++k) \
;         acc[ai][bj][m][n] = mma1v<MMAV>(Bt[n][k], At[m][k], acc[ai][bj][m][n]); __builtin_amdgcn_s_setprio(0); } while (0)
; #define PG8_WAIT_V(n) asm volatile("s_waitcnt vmcnt(" #n ")" ::: "memory")
; #define PG8_WAIT_L(n) asm volatile("s_waitcnt lgkmcnt(" #n ")" ::: "memory")
; #define PG8_BAR __builtin_amdgcn_s_barrier()
; #define PG8_SCHED __builtin_amdgcn_sched_barrier(0)
;     ...
;             PG8_LDB(B0, 1, 0); PG8_LDB(B1, 1, 1); PG8_SCHED; PG8_LDA(At, 1, 0); PG8_STAGE(PG8_SA(0, 1), a2 + hstep, voffA);
;             PG8_WAIT_V(8); PG8_WAIT_L(0); PG8_BAR; PG8_MMA(0, 0, At, B0); PG8_MMA(0, 1, At, B1); PG8_BAR; PG8_SCHED;
;             PG8_LDA(At, 1, 1); PG8_STAGE(PG8_SB(1, 0), b3, voffB); PG8_STAGE(PG8_SB(1, 1), b3 + hstepB, voffB); PG8_STAGE(PG8_SA(1, 0), a3, voffA);
;             PG8_WAIT_V(8); PG8_WAIT_L(0); PG8_BAR; PG8_MMA(1, 0, At, B0); PG8_MMA(1, 1, At, B1); PG8_BAR; PG8_SCHED;
	s_add_u32 s10, s8, 0x8000
	s_addc_u32 s11, s9, 0
	s_add_i32 s80, s80, s53
	v_lshl_add_u64 v[252:253], s[10:11], 0, v[142:143]
	s_mov_b32 m0, s80
	ds_read_b128 v[216:219], v175 offset:49152
	ds_read_b128 v[220:223], v175 offset:50176
	ds_read_b128 v[224:227], v175 offset:51200
	ds_read_b128 v[228:231], v175 offset:52224
	ds_read_b128 v[232:235], v175 offset:53248
	ds_read_b128 v[236:239], v175 offset:54272
	ds_read_b128 v[240:243], v175 offset:55296
	ds_read_b128 v[244:247], v175 offset:56320
	global_load_lds_dwordx4 v[252:253], off
	s_add_i32 m0, s80, 0x2000
	s_add_u32 s8, s8, 0xc000
	v_lshl_add_u64 v[252:253], s[10:11], 0, v[146:147]
	s_addc_u32 s9, s9, 0
	s_add_i32 s10, s81, s53
	global_load_lds_dwordx4 v[252:253], off
	v_lshl_add_u64 v[252:253], s[8:9], 0, v[142:143]
	s_mov_b32 m0, s10
	v_lshl_add_u64 v[248:249], v[248:249], 0, s[78:79]
	global_load_lds_dwordx4 v[252:253], off
	v_lshl_add_u64 v[252:253], s[8:9], 0, v[146:147]
	s_add_i32 m0, s10, 0x2000
	s_nop 0
	global_load_lds_dwordx4 v[252:253], off
	s_mov_b32 m0, s63
	s_nop 0
	global_load_lds_dwordx4 v[248:249], off
	v_lshl_add_u64 v[248:249], v[250:251], 0, s[78:79]
	s_mov_b32 m0, s64
	s_nop 0
	global_load_lds_dwordx4 v[248:249], off
	s_waitcnt vmcnt(8)
	s_waitcnt lgkmcnt(0)
	s_barrier
	s_setprio 1
	s_waitcnt lgkmcnt(0)
	v_mfma_f32_16x16x32_bf16 v[62:65], v[130:133], v[216:219], v[62:65]
	v_mfma_f32_16x16x32_bf16 v[58:61], v[138:141], v[216:219], v[58:61]
	v_mfma_f32_16x16x32_bf16 v[46:49], v[130:133], v[224:227], v[46:49]
	v_mfma_f32_16x16x32_bf16 v[42:45], v[138:141], v[224:227], v[42:45]
	v_mfma_f32_16x16x32_bf16 v[30:33], v[130:133], v[232:235], v[30:33]
	v_mfma_f32_16x16x32_bf16 v[26:29], v[138:141], v[232:235], v[26:29]
	v_mfma_f32_16x16x32_bf16 v[14:17], v[130:133], v[240:243], v[14:17]
	v_mfma_f32_16x16x32_bf16 v[10:13], v[138:141], v[240:243], v[10:13]
	v_mfma_f32_16x16x32_bf16 v[62:65], v[134:137], v[220:223], v[62:65]
	v_mfma_f32_16x16x32_bf16 v[58:61], v[154:157], v[220:223], v[58:61]
	v_mfma_f32_16x16x32_bf16 v[46:49], v[134:137], v[228:231], v[46:49]
	v_mfma_f32_16x16x32_bf16 v[42:45], v[154:157], v[228:231], v[42:45]
	v_mfma_f32_16x16x32_bf16 v[30:33], v[134:137], v[236:239], v[30:33]
	v_mfma_f32_16x16x32_bf16 v[26:29], v[154:157], v[236:239], v[26:29]
	v_mfma_f32_16x16x32_bf16 v[14:17], v[134:137], v[244:247], v[14:17]
	v_mfma_f32_16x16x32_bf16 v[10:13], v[154:157], v[244:247], v[10:13]
	s_setprio 0
	s_setprio 1
	v_mfma_f32_16x16x32_bf16 v[54:57], v[176:179], v[216:219], v[54:57]
	v_mfma_f32_16x16x32_bf16 v[50:53], v[184:187], v[216:219], v[50:53]
	v_mfma_f32_16x16x32_bf16 v[38:41], v[176:179], v[224:227], v[38:41]
	v_mfma_f32_16x16x32_bf16 v[34:37], v[184:187], v[224:227], v[34:37]
	v_mfma_f32_16x16x32_bf16 v[22:25], v[176:179], v[232:235], v[22:25]
	v_mfma_f32_16x16x32_bf16 v[18:21], v[184:187], v[232:235], v[18:21]
	v_mfma_f32_16x16x32_bf16 v[6:9], v[176:179], v[240:243], v[6:9]
	v_mfma_f32_16x16x32_bf16 v[2:5], v[184:187], v[240:243], v[2:5]
	v_mfma_f32_16x16x32_bf16 v[54:57], v[180:183], v[220:223], v[54:57]
	v_mfma_f32_16x16x32_bf16 v[50:53], v[188:191], v[220:223], v[50:53]
	v_mfma_f32_16x16x32_bf16 v[38:41], v[180:183], v[228:231], v[38:41]
	v_mfma_f32_16x16x32_bf16 v[34:37], v[188:191], v[228:231], v[34:37]
	v_mfma_f32_16x16x32_bf16 v[22:25], v[180:183], v[236:239], v[22:25]
	v_mfma_f32_16x16x32_bf16 v[18:21], v[188:191], v[236:239], v[18:21]
	v_mfma_f32_16x16x32_bf16 v[6:9], v[180:183], v[244:247], v[6:9]
	v_mfma_f32_16x16x32_bf16 v[2:5], v[188:191], v[244:247], v[2:5]
	s_setprio 0
	s_barrier
	s_add_i32 s43, s43, 2
	s_add_u32 s41, s41, 0x10000
	s_addc_u32 s42, s42, 0
	s_add_u32 s0, s0, 0x100
	s_addc_u32 s1, s1, 0

; #define PG8_STAGE(bufoff, gbase, voff) do { _Pragma("unroll") for (int _i = 0; _i < 2; ++_i) \
;         __builtin_amdgcn_global_load_lds((const unsigned*)((const char*)(gbase) + (voff)[_i]), (PG8_LAS unsigned*)(lds + (bufoff) + ldsw + _i * 8192), 16, 0, 0); } while (0)
; #define PG8_LDA(dst, b, h) do { _Pragma("unroll") for (int m = 0; m < 4; ++m) _Pragma("unroll") for (int k = 0; k < 2; ++k) dst[m][k] = *(const PG8_LAS frag_t*)(lds + PG8_SA(b, h) + aoff + m * 2048 + k * 1024); } while (0)
; #define PG8_LDB(dst, b, h) do { _Pragma("unroll") for (int n = 0; n < 2; ++n) _Pragma("unroll") for (int k = 0; k < 2; ++k) dst[n][k] = *(const PG8_LAS frag_t*)(lds + PG8_SB(b, h) + boff + n * 2048 + k * 1024); } while (0)
; #define PG8_MMA(ai, bj, At, Bt) do { __builtin_amdgcn_s_setprio(1); _Pragma("unroll") for (int m = 0; m < 4; ++m) _Pragma("unroll") for (int n = 0; n < 2; ++n) _Pragma("unroll") for (int k = 0; k < 2; ++k) \
;         acc[ai][bj][m][n] = mma1v<MMAV>(Bt[n][k], At[m][k], acc[ai][bj][m][n]); __builtin_amdgcn_s_setprio(0); } while (0)
; #define PG8_WAIT_V(n) asm volatile("s_waitcnt vmcnt(" #n ")" ::: "memory")
; #define PG8_WAIT_L(n) asm volatile("s_waitcnt lgkmcnt(" #n ")" ::: "memory")
;     ...
;         const bool has_next = S.next(ui + 1, nxt);
;         const char* nA = has_next ? (const char*)g.A + (size_t)nxt.pm * tstep : cA; const char* nB = has_next ? (const char*)g.Bt + (size_t)nxt.pn * tstep : cB;
;         for (int t = 0; t < nt; t += 2) {
;             const bool last = (t == nt - 2);
;             const char* a1 = cA + (size_t)(t + 1) * kstep;
;             const char* a2 = last ? nA : cA + (size_t)(t + 2) * kstep; const char* b2 = last ? nB : cB + (size_t)(t + 2) * kstepB;
;             const char* a3 = a2 + kstep; const char* b3 = b2 + kstepB;
;             if (last && has_next) S.a_ready(nxt);
;             if constexpr (SP2) {
;             PG8_LDB(B0, 0, 0); PG8_LDB(B1, 0, 1); PG8_SCHED; PG8_LDA(At, 0, 0); PG8_STAGE(PG8_SA(1, 1), a1 + hstep, voffA);
;             PG8_WAIT_V(8); PG8_WAIT_L(0); PG8_BAR; PG8_MMA(0, 0, At, B0); PG8_MMA(0, 1, At, B1); PG8_BAR; PG8_SCHED;
;             PG8_LDA(At, 0, 1); PG8_STAGE(PG8_SB(0, 0), b2, voffB); PG8_STAGE(PG8_SB(0, 1), b2 + hstepB, voffB); PG8_STAGE(PG8_SA(0, 0), a2, voffA);
;             PG8_WAIT_V(8); PG8_WAIT_L(0); PG8_BAR; PG8_MMA(1, 0, At, B0); PG8_MMA(1, 1, At, B1); PG8_BAR; PG8_SCHED;
.LBB0_1023:
	s_ashr_i32 s17, s16, 31
	s_lshl_b64 s[18:19], s[16:17], 20
	s_add_u32 s18, s34, s18
	s_addc_u32 s19, s35, s19
	s_and_b64 s[20:21], s[4:5], exec
	s_cselect_b32 s7, s19, s27
	s_cselect_b32 s17, s18, s26
	s_ashr_i32 s15, s14, 31
	s_lshl_b64 s[20:21], s[14:15], 20
	s_add_u32 s20, s36, s20
	s_addc_u32 s21, s37, s21
	s_and_b64 s[28:29], s[4:5], exec
	s_cselect_b32 s15, s21, s25
	s_cselect_b32 s23, s20, s24
	s_add_u32 s51, s24, 0x10000
	s_addc_u32 s52, s25, 0
	s_add_u32 s24, s26, 0x80080
	s_addc_u32 s25, s27, 0
	s_mov_b32 s53, -2
	s_waitcnt lgkmcnt(0)
	s_add_u32 s26, s24, 0xfff80080
	s_addc_u32 s27, s25, -1
	s_add_i32 s54, 0, 0x10000
	s_cmp_eq_u32 s53, 28
	s_cselect_b32 s29, s7, s27
	s_cselect_b32 s28, s17, s26
	v_add_u32_e32 v148, s54, v151
	s_cselect_b32 s27, s15, s52
	s_cselect_b32 s26, s23, s51
	s_add_i32 s56, 0, 0x14000
	ds_read_b128 v[130:133], v148
	ds_read_b128 v[134:137], v148 offset:1024
	ds_read_b128 v[154:157], v148 offset:2048
	ds_read_b128 v[158:161], v148 offset:3072
	v_add_u32_e32 v148, s56, v151
	ds_read_b128 v[174:177], v148
	ds_read_b128 v[178:181], v148 offset:1024
	ds_read_b128 v[182:185], v148 offset:2048
	ds_read_b128 v[186:189], v148 offset:3072
	v_lshl_add_u64 v[148:149], s[24:25], 0, v[144:145]
	s_add_i32 m0, s39, 0xc000
	ds_read_b128 v[216:219], v152
	ds_read_b128 v[220:223], v152 offset:1024
	ds_read_b128 v[224:227], v152 offset:2048
	ds_read_b128 v[228:231], v152 offset:3072
	ds_read_b128 v[232:235], v152 offset:4096
	ds_read_b128 v[236:239], v152 offset:5120
	ds_read_b128 v[240:243], v152 offset:6144
	ds_read_b128 v[244:247], v152 offset:7168
	global_load_lds_dwordx4 v[148:149], off
	v_lshl_add_u64 v[148:149], s[24:25], 0, v[146:147]
	s_add_i32 m0, s39, 0xe000
	s_nop 0
	global_load_lds_dwordx4 v[148:149], off
	s_waitcnt vmcnt(8)
	s_waitcnt lgkmcnt(0)
	s_barrier
	s_setprio 1
	s_waitcnt lgkmcnt(0)
	v_mfma_f32_16x16x32_bf16 v[126:129], v[130:133], v[216:219], 0
	v_mfma_f32_16x16x32_bf16 v[122:125], v[154:157], v[216:219], 0
	v_mfma_f32_16x16x32_bf16 v[110:113], v[130:133], v[224:227], 0
	v_mfma_f32_16x16x32_bf16 v[106:109], v[154:157], v[224:227], 0
	v_mfma_f32_16x16x32_bf16 v[94:97], v[130:133], v[232:235], 0
	v_mfma_f32_16x16x32_bf16 v[90:93], v[154:157], v[232:235], 0
	v_mfma_f32_16x16x32_bf16 v[78:81], v[130:133], v[240:243], 0
	v_mfma_f32_16x16x32_bf16 v[74:77], v[154:157], v[240:243], 0
	v_mfma_f32_16x16x32_bf16 v[126:129], v[134:137], v[220:223], v[126:129]
	v_mfma_f32_16x16x32_bf16 v[122:125], v[158:161], v[220:223], v[122:125]
	v_mfma_f32_16x16x32_bf16 v[110:113], v[134:137], v[228:231], v[110:113]
	v_mfma_f32_16x16x32_bf16 v[106:109], v[158:161], v[228:231], v[106:109]
	v_mfma_f32_16x16x32_bf16 v[94:97], v[134:137], v[236:239], v[94:97]
	v_mfma_f32_16x16x32_bf16 v[90:93], v[158:161], v[236:239], v[90:93]
	v_mfma_f32_16x16x32_bf16 v[78:81], v[134:137], v[244:247], v[78:81]
	v_mfma_f32_16x16x32_bf16 v[74:77], v[158:161], v[244:247], v[74:77]
	s_setprio 0
	s_setprio 1
	v_mfma_f32_16x16x32_bf16 v[118:121], v[174:177], v[216:219], 0
	v_mfma_f32_16x16x32_bf16 v[114:117], v[182:185], v[216:219], 0
	v_mfma_f32_16x16x32_bf16 v[102:105], v[174:177], v[224:227], 0
	v_mfma_f32_16x16x32_bf16 v[98:101], v[182:185], v[224:227], 0
	v_mfma_f32_16x16x32_bf16 v[86:89], v[174:177], v[232:235], 0
	v_mfma_f32_16x16x32_bf16 v[82:85], v[182:185], v[232:235], 0
	v_mfma_f32_16x16x32_bf16 v[70:73], v[174:177], v[240:243], 0
	v_mfma_f32_16x16x32_bf16 v[66:69], v[182:185], v[240:243], 0
	v_mfma_f32_16x16x32_bf16 v[118:121], v[178:181], v[220:223], v[118:121]
	v_mfma_f32_16x16x32_bf16 v[114:117], v[186:189], v[220:223], v[114:117]
	v_mfma_f32_16x16x32_bf16 v[102:105], v[178:181], v[228:231], v[102:105]
	v_mfma_f32_16x16x32_bf16 v[98:101], v[186:189], v[228:231], v[98:101]
	v_mfma_f32_16x16x32_bf16 v[86:89], v[178:181], v[236:239], v[86:89]
	v_mfma_f32_16x16x32_bf16 v[82:85], v[186:189], v[236:239], v[82:85]
	v_mfma_f32_16x16x32_bf16 v[70:73], v[178:181], v[244:247], v[70:73]
	v_mfma_f32_16x16x32_bf16 v[66:69], v[186:189], v[244:247], v[66:69]
	s_setprio 0
	s_barrier
	s_add_i32 s54, s54, s38
	v_lshl_add_u64 v[148:149], s[26:27], 0, v[138:139]
	s_mov_b32 m0, s54
	ds_read_b128 v[216:219], v152 offset:16384
	ds_read_b128 v[220:223], v152 offset:17408
	ds_read_b128 v[224:227], v152 offset:18432
	ds_read_b128 v[228:231], v152 offset:19456
	ds_read_b128 v[232:235], v152 offset:20480
	ds_read_b128 v[236:239], v152 offset:21504
	ds_read_b128 v[240:243], v152 offset:22528
	ds_read_b128 v[244:247], v152 offset:23552
	global_load_lds_dwordx4 v[148:149], off
	s_add_i32 m0, s54, 0x2000
	s_add_u32 s54, s26, 0x4000
	v_lshl_add_u64 v[148:149], s[26:27], 0, v[142:143]
	s_addc_u32 s55, s27, 0
	s_add_i32 s56, s56, s38
	global_load_lds_dwordx4 v[148:149], off
	v_lshl_add_u64 v[148:149], s[54:55], 0, v[138:139]
	s_mov_b32 m0, s56
	v_lshl_add_u64 v[190:191], s[28:29], 0, v[140:141]
	global_load_lds_dwordx4 v[148:149], off
	v_lshl_add_u64 v[148:149], s[54:55], 0, v[142:143]
	s_add_i32 m0, s56, 0x2000
	s_nop 0
	global_load_lds_dwordx4 v[148:149], off
	v_lshl_add_u64 v[148:149], s[28:29], 0, v[162:163]
	s_mov_b32 m0, s39
	s_nop 0
	global_load_lds_dwordx4 v[148:149], off
	s_mov_b32 m0, s40
	s_nop 0
	global_load_lds_dwordx4 v[190:191], off
	s_waitcnt vmcnt(8)
	s_waitcnt lgkmcnt(0)
	s_barrier
; #define PG8_STAGE(bufoff, gbase, voff) do { _Pragma("unroll") for (int _i = 0; _i < 2; ++_i) \
;         __builtin_amdgcn_global_load_lds((const unsigned*)((const char*)(gbase) + (voff)[_i]), (PG8_LAS unsigned*)(lds + (bufoff) + ldsw + _i * 8192), 16, 0, 0); } while (0)
; #define PG8_LDA(dst, b, h) do { _Pragma("unroll") for (int m = 0; m < 4; ++m) _Pragma("unroll") for (int k = 0; k < 2; ++k) dst[m][k] = *(const PG8_LAS frag_t*)(lds + PG8_SA(b, h) + aoff + m * 2048 + k * 1024); } while (0)
; #define PG8_LDB(dst, b, h) do { _Pragma("unroll") for (int n = 0; n < 2; ++n) _Pragma("unroll") for (int k = 0; k < 2; ++k) dst[n][k] = *(const PG8_LAS frag_t*)(lds + PG8_SB(b, h) + boff + n * 2048 + k * 1024); } while (0)
; #define PG8_MMA(ai, bj, At, Bt) do { __builtin_amdgcn_s_setprio(1); _Pragma("unroll") for (int m = 0; m < 4; ++m) _Pragma("unroll") for (int n = 0; n < 2; ++n) _Pragma("unroll") for (int k = 0; k < 2; ++k) \
;         acc[ai][bj][m][n] = mma1v<MMAV>(Bt[n][k], At[m][k], acc[ai][bj][m][n]); __builtin_amdgcn_s_setprio(0); } while (0)
; #define PG8_WAIT_V(n) asm volatile("s_waitcnt vmcnt(" #n ")" ::: "memory")
; #define PG8_WAIT_L(n) asm volatile("s_waitcnt lgkmcnt(" #n ")" ::: "memory")
; #define PG8_BAR __builtin_amdgcn_s_barrier()
; #define PG8_SCHED __builtin_amdgcn_sched_barrier(0)
;     ...
;             PG8_WAIT_V(8); PG8_WAIT_L(0); PG8_BAR; PG8_MMA(0, 0, At, B0); PG8_MMA(0, 1, At, B1); PG8_BAR; PG8_SCHED;
;             PG8_LDA(At, 0, 1); PG8_STAGE(PG8_SB(0, 0), b2, voffB); PG8_STAGE(PG8_SB(0, 1), b2 + hstepB, voffB); PG8_STAGE(PG8_SA(0, 0), a2, voffA);
;             PG8_WAIT_V(8); PG8_WAIT_L(0); PG8_BAR; PG8_MMA(1, 0, At, B0); PG8_MMA(1, 1, At, B1); PG8_BAR; PG8_SCHED;
;             PG8_LDB(B0, 1, 0); PG8_LDB(B1, 1, 1); PG8_SCHED; PG8_LDA(At, 1, 0); PG8_STAGE(PG8_SA(0, 1), a2 + hstep, voffA);
;             PG8_WAIT_V(8); PG8_WAIT_L(0); PG8_BAR; PG8_MMA(0, 0, At, B0); PG8_MMA(0, 1, At, B1); PG8_BAR; PG8_SCHED;
	s_setprio 1
	s_waitcnt lgkmcnt(0)
	v_mfma_f32_16x16x32_bf16 v[62:65], v[130:133], v[216:219], 0
	v_mfma_f32_16x16x32_bf16 v[58:61], v[154:157], v[216:219], 0
	v_mfma_f32_16x16x32_bf16 v[46:49], v[130:133], v[224:227], 0
	v_mfma_f32_16x16x32_bf16 v[42:45], v[154:157], v[224:227], 0
	v_mfma_f32_16x16x32_bf16 v[30:33], v[130:133], v[232:235], 0
	v_mfma_f32_16x16x32_bf16 v[26:29], v[154:157], v[232:235], 0
	v_mfma_f32_16x16x32_bf16 v[14:17], v[130:133], v[240:243], 0
	v_mfma_f32_16x16x32_bf16 v[10:13], v[154:157], v[240:243], 0
	v_mfma_f32_16x16x32_bf16 v[62:65], v[134:137], v[220:223], v[62:65]
	v_mfma_f32_16x16x32_bf16 v[58:61], v[158:161], v[220:223], v[58:61]
	v_mfma_f32_16x16x32_bf16 v[46:49], v[134:137], v[228:231], v[46:49]
	v_mfma_f32_16x16x32_bf16 v[42:45], v[158:161], v[228:231], v[42:45]
	v_mfma_f32_16x16x32_bf16 v[30:33], v[134:137], v[236:239], v[30:33]
	v_mfma_f32_16x16x32_bf16 v[26:29], v[158:161], v[236:239], v[26:29]
	v_mfma_f32_16x16x32_bf16 v[14:17], v[134:137], v[244:247], v[14:17]
	v_mfma_f32_16x16x32_bf16 v[10:13], v[158:161], v[244:247], v[10:13]
	s_setprio 0
	s_setprio 1
	v_mfma_f32_16x16x32_bf16 v[54:57], v[174:177], v[216:219], 0
	v_mfma_f32_16x16x32_bf16 v[50:53], v[182:185], v[216:219], 0
	v_mfma_f32_16x16x32_bf16 v[38:41], v[174:177], v[224:227], 0
	v_mfma_f32_16x16x32_bf16 v[34:37], v[182:185], v[224:227], 0
	v_mfma_f32_16x16x32_bf16 v[22:25], v[174:177], v[232:235], 0
	v_mfma_f32_16x16x32_bf16 v[18:21], v[182:185], v[232:235], 0
	v_mfma_f32_16x16x32_bf16 v[6:9], v[174:177], v[240:243], 0
	v_mfma_f32_16x16x32_bf16 v[2:5], v[182:185], v[240:243], 0
	v_mfma_f32_16x16x32_bf16 v[54:57], v[178:181], v[220:223], v[54:57]
	v_mfma_f32_16x16x32_bf16 v[50:53], v[186:189], v[220:223], v[50:53]
	v_mfma_f32_16x16x32_bf16 v[38:41], v[178:181], v[228:231], v[38:41]
	v_mfma_f32_16x16x32_bf16 v[34:37], v[186:189], v[228:231], v[34:37]
	v_mfma_f32_16x16x32_bf16 v[22:25], v[178:181], v[236:239], v[22:25]
	v_mfma_f32_16x16x32_bf16 v[18:21], v[186:189], v[236:239], v[18:21]
	v_mfma_f32_16x16x32_bf16 v[6:9], v[178:181], v[244:247], v[6:9]
	v_mfma_f32_16x16x32_bf16 v[2:5], v[186:189], v[244:247], v[2:5]
	s_setprio 0
	s_barrier
	s_add_i32 s54, 0, 0x18000
	v_add_u32_e32 v153, s54, v151
	s_add_i32 s55, 0, 0x1c000
	ds_read_b128 v[130:133], v153
	ds_read_b128 v[134:137], v153 offset:1024
	ds_read_b128 v[154:157], v153 offset:2048
	ds_read_b128 v[158:161], v153 offset:3072
	v_add_u32_e32 v153, s55, v151
	ds_read_b128 v[174:177], v153
	ds_read_b128 v[178:181], v153 offset:1024
	ds_read_b128 v[182:185], v153 offset:2048
	ds_read_b128 v[186:189], v153 offset:3072
	s_add_u32 s28, s28, 0x80000
	s_addc_u32 s29, s29, 0
	s_mov_b32 m0, s41
	v_lshl_add_u64 v[248:249], s[28:29], 0, v[162:163]
	ds_read_b128 v[216:219], v152 offset:32768
	ds_read_b128 v[220:223], v152 offset:33792
	ds_read_b128 v[224:227], v152 offset:34816
	ds_read_b128 v[228:231], v152 offset:35840
	ds_read_b128 v[232:235], v152 offset:36864
	ds_read_b128 v[236:239], v152 offset:37888
	ds_read_b128 v[240:243], v152 offset:38912
	ds_read_b128 v[244:247], v152 offset:39936
	global_load_lds_dwordx4 v[248:249], off
	v_lshl_add_u64 v[248:249], s[28:29], 0, v[140:141]
	s_mov_b32 m0, s42
	s_nop 0
	global_load_lds_dwordx4 v[248:249], off
	s_waitcnt vmcnt(8)
	s_waitcnt lgkmcnt(0)
	s_barrier
	s_setprio 1
	s_waitcnt lgkmcnt(0)
	v_mfma_f32_16x16x32_bf16 v[126:129], v[130:133], v[216:219], v[126:129]
	v_mfma_f32_16x16x32_bf16 v[122:125], v[154:157], v[216:219], v[122:125]
	v_mfma_f32_16x16x32_bf16 v[110:113], v[130:133], v[224:227], v[110:113]
	v_mfma_f32_16x16x32_bf16 v[106:109], v[154:157], v[224:227], v[106:109]
	v_mfma_f32_16x16x32_bf16 v[94:97], v[130:133], v[232:235], v[94:97]
	v_mfma_f32_16x16x32_bf16 v[90:93], v[154:157], v[232:235], v[90:93]
	v_mfma_f32_16x16x32_bf16 v[78:81], v[130:133], v[240:243], v[78:81]
	v_mfma_f32_16x16x32_bf16 v[74:77], v[154:157], v[240:243], v[74:77]
	v_mfma_f32_16x16x32_bf16 v[126:129], v[134:137], v[220:223], v[126:129]
	v_mfma_f32_16x16x32_bf16 v[122:125], v[158:161], v[220:223], v[122:125]
	v_mfma_f32_16x16x32_bf16 v[110:113], v[134:137], v[228:231], v[110:113]
	v_mfma_f32_16x16x32_bf16 v[106:109], v[158:161], v[228:231], v[106:109]
	v_mfma_f32_16x16x32_bf16 v[94:97], v[134:137], v[236:239], v[94:97]
	v_mfma_f32_16x16x32_bf16 v[90:93], v[158:161], v[236:239], v[90:93]
	v_mfma_f32_16x16x32_bf16 v[78:81], v[134:137], v[244:247], v[78:81]
	v_mfma_f32_16x16x32_bf16 v[74:77], v[158:161], v[244:247], v[74:77]
	s_setprio 0
	s_setprio 1
	v_mfma_f32_16x16x32_bf16 v[118:121], v[174:177], v[216:219], v[118:121]
	v_mfma_f32_16x16x32_bf16 v[114:117], v[182:185], v[216:219], v[114:117]
	v_mfma_f32_16x16x32_bf16 v[102:105], v[174:177], v[224:227], v[102:105]
	v_mfma_f32_16x16x32_bf16 v[98:101], v[182:185], v[224:227], v[98:101]
	v_mfma_f32_16x16x32_bf16 v[86:89], v[174:177], v[232:235], v[86:89]
	v_mfma_f32_16x16x32_bf16 v[82:85], v[182:185], v[232:235], v[82:85]
	v_mfma_f32_16x16x32_bf16 v[70:73], v[174:177], v[240:243], v[70:73]
	v_mfma_f32_16x16x32_bf16 v[66:69], v[182:185], v[240:243], v[66:69]
	v_mfma_f32_16x16x32_bf16 v[118:121], v[178:181], v[220:223], v[118:121]
	v_mfma_f32_16x16x32_bf16 v[114:117], v[186:189], v[220:223], v[114:117]
	v_mfma_f32_16x16x32_bf16 v[102:105], v[178:181], v[228:231], v[102:105]
	v_mfma_f32_16x16x32_bf16 v[98:101], v[186:189], v[228:231], v[98:101]
	v_mfma_f32_16x16x32_bf16 v[86:89], v[178:181], v[236:239], v[86:89]
	v_mfma_f32_16x16x32_bf16 v[82:85], v[186:189], v[236:239], v[82:85]
	v_mfma_f32_16x16x32_bf16 v[70:73], v[178:181], v[244:247], v[70:73]
	v_mfma_f32_16x16x32_bf16 v[66:69], v[186:189], v[244:247], v[66:69]
	s_setprio 0
	s_barrier
; #define PG8_STAGE(bufoff, gbase, voff) do { _Pragma("unroll") for (int _i = 0; _i < 2; ++_i) \
;         __builtin_amdgcn_global_load_lds((const unsigned*)((const char*)(gbase) + (voff)[_i]), (PG8_LAS unsigned*)(lds + (bufoff) + ldsw + _i * 8192), 16, 0, 0); } while (0)
; #define PG8_LDA(dst, b, h) do { _Pragma("unroll") for (int m = 0; m < 4; ++m) _Pragma("unroll") for (int k = 0; k < 2; ++k) dst[m][k] = *(const PG8_LAS frag_t*)(lds + PG8_SA(b, h) + aoff + m * 2048 + k * 1024); } while (0)
; #define PG8_LDB(dst, b, h) do { _Pragma("unroll") for (int n = 0; n < 2; ++n) _Pragma("unroll") for (int k = 0; k < 2; ++k) dst[n][k] = *(const PG8_LAS frag_t*)(lds + PG8_SB(b, h) + boff + n * 2048 + k * 1024); } while (0)
; #define PG8_MMA(ai, bj, At, Bt) do { __builtin_amdgcn_s_setprio(1); _Pragma("unroll") for (int m = 0; m < 4; ++m) _Pragma("unroll") for (int n = 0; n < 2; ++n) _Pragma("unroll") for (int k = 0; k < 2; ++k) \
;         acc[ai][bj][m][n] = mma1v<MMAV>(Bt[n][k], At[m][k], acc[ai][bj][m][n]); __builtin_amdgcn_s_setprio(0); } while (0)
; #define PG8_WAIT_V(n) asm volatile("s_waitcnt vmcnt(" #n ")" ::: "memory")
; #define PG8_WAIT_L(n) asm volatile("s_waitcnt lgkmcnt(" #n ")" ::: "memory")
; #define PG8_BAR __builtin_amdgcn_s_barrier()
; #define PG8_SCHED __builtin_amdgcn_sched_barrier(0)
;     ...
;             PG8_LDB(B0, 1, 0); PG8_LDB(B1, 1, 1); PG8_SCHED; PG8_LDA(At, 1, 0); PG8_STAGE(PG8_SA(0, 1), a2 + hstep, voffA);
;             PG8_WAIT_V(8); PG8_WAIT_L(0); PG8_BAR; PG8_MMA(0, 0, At, B0); PG8_MMA(0, 1, At, B1); PG8_BAR; PG8_SCHED;
;             PG8_LDA(At, 1, 1); PG8_STAGE(PG8_SB(1, 0), b3, voffB); PG8_STAGE(PG8_SB(1, 1), b3 + hstepB, voffB); PG8_STAGE(PG8_SA(1, 0), a3, voffA);
;             PG8_WAIT_V(8); PG8_WAIT_L(0); PG8_BAR; PG8_MMA(1, 0, At, B0); PG8_MMA(1, 1, At, B1); PG8_BAR; PG8_SCHED;
	s_add_u32 s28, s26, 0x8000
	s_addc_u32 s29, s27, 0
	s_add_i32 s54, s54, s38
	v_lshl_add_u64 v[248:249], s[28:29], 0, v[138:139]
	s_mov_b32 m0, s54
	ds_read_b128 v[216:219], v152 offset:49152
	ds_read_b128 v[220:223], v152 offset:50176
	ds_read_b128 v[224:227], v152 offset:51200
	ds_read_b128 v[228:231], v152 offset:52224
	ds_read_b128 v[232:235], v152 offset:53248
	ds_read_b128 v[236:239], v152 offset:54272
	ds_read_b128 v[240:243], v152 offset:55296
	ds_read_b128 v[244:247], v152 offset:56320
	global_load_lds_dwordx4 v[248:249], off
	s_add_i32 m0, s54, 0x2000
	s_add_u32 s26, s26, 0xc000
	v_lshl_add_u64 v[248:249], s[28:29], 0, v[142:143]
	s_addc_u32 s27, s27, 0
	s_add_i32 s28, s55, s38
	global_load_lds_dwordx4 v[248:249], off
	v_lshl_add_u64 v[248:249], s[26:27], 0, v[138:139]
	s_mov_b32 m0, s28
	v_lshl_add_u64 v[148:149], v[148:149], 0, s[78:79]
	global_load_lds_dwordx4 v[248:249], off
	v_lshl_add_u64 v[248:249], s[26:27], 0, v[142:143]
	s_add_i32 m0, s28, 0x2000
	s_nop 0
	global_load_lds_dwordx4 v[248:249], off
	s_mov_b32 m0, s46
	s_nop 0
	global_load_lds_dwordx4 v[148:149], off
	v_lshl_add_u64 v[148:149], v[190:191], 0, s[78:79]
	s_mov_b32 m0, s47
	s_nop 0
	global_load_lds_dwordx4 v[148:149], off
	s_waitcnt vmcnt(8)
	s_waitcnt lgkmcnt(0)
	s_barrier
	s_setprio 1
	s_waitcnt lgkmcnt(0)
	v_mfma_f32_16x16x32_bf16 v[62:65], v[130:133], v[216:219], v[62:65]
	v_mfma_f32_16x16x32_bf16 v[58:61], v[154:157], v[216:219], v[58:61]
	v_mfma_f32_16x16x32_bf16 v[46:49], v[130:133], v[224:227], v[46:49]
	v_mfma_f32_16x16x32_bf16 v[42:45], v[154:157], v[224:227], v[42:45]
	v_mfma_f32_16x16x32_bf16 v[30:33], v[130:133], v[232:235], v[30:33]
	v_mfma_f32_16x16x32_bf16 v[26:29], v[154:157], v[232:235], v[26:29]
	v_mfma_f32_16x16x32_bf16 v[14:17], v[130:133], v[240:243], v[14:17]
	v_mfma_f32_16x16x32_bf16 v[10:13], v[154:157], v[240:243], v[10:13]
	v_mfma_f32_16x16x32_bf16 v[62:65], v[134:137], v[220:223], v[62:65]
	v_mfma_f32_16x16x32_bf16 v[58:61], v[158:161], v[220:223], v[58:61]
	v_mfma_f32_16x16x32_bf16 v[46:49], v[134:137], v[228:231], v[46:49]
	v_mfma_f32_16x16x32_bf16 v[42:45], v[158:161], v[228:231], v[42:45]
	v_mfma_f32_16x16x32_bf16 v[30:33], v[134:137], v[236:239], v[30:33]
	v_mfma_f32_16x16x32_bf16 v[26:29], v[158:161], v[236:239], v[26:29]
	v_mfma_f32_16x16x32_bf16 v[14:17], v[134:137], v[244:247], v[14:17]
	v_mfma_f32_16x16x32_bf16 v[10:13], v[158:161], v[244:247], v[10:13]
	s_setprio 0
	s_setprio 1
	v_mfma_f32_16x16x32_bf16 v[54:57], v[174:177], v[216:219], v[54:57]
	v_mfma_f32_16x16x32_bf16 v[50:53], v[182:185], v[216:219], v[50:53]
	v_mfma_f32_16x16x32_bf16 v[38:41], v[174:177], v[224:227], v[38:41]
	v_mfma_f32_16x16x32_bf16 v[34:37], v[182:185], v[224:227], v[34:37]
	v_mfma_f32_16x16x32_bf16 v[22:25], v[174:177], v[232:235], v[22:25]
	v_mfma_f32_16x16x32_bf16 v[18:21], v[182:185], v[232:235], v[18:21]
	v_mfma_f32_16x16x32_bf16 v[6:9], v[174:177], v[240:243], v[6:9]
	v_mfma_f32_16x16x32_bf16 v[2:5], v[182:185], v[240:243], v[2:5]
	v_mfma_f32_16x16x32_bf16 v[54:57], v[178:181], v[220:223], v[54:57]
	v_mfma_f32_16x16x32_bf16 v[50:53], v[186:189], v[220:223], v[50:53]
	v_mfma_f32_16x16x32_bf16 v[38:41], v[178:181], v[228:231], v[38:41]
	v_mfma_f32_16x16x32_bf16 v[34:37], v[186:189], v[228:231], v[34:37]
	v_mfma_f32_16x16x32_bf16 v[22:25], v[178:181], v[236:239], v[22:25]
	v_mfma_f32_16x16x32_bf16 v[18:21], v[186:189], v[236:239], v[18:21]
	v_mfma_f32_16x16x32_bf16 v[6:9], v[178:181], v[244:247], v[6:9]
	v_mfma_f32_16x16x32_bf16 v[2:5], v[186:189], v[244:247], v[2:5]
	s_setprio 0
	s_barrier
	s_add_i32 s53, s53, 2
	s_add_u32 s51, s51, 0x10000
	s_addc_u32 s52, s52, 0
	s_add_u32 s24, s24, 0x100
	s_addc_u32 s25, s25, 0

; #define PG8_STAGE(bufoff, gbase, voff) do { _Pragma("unroll") for (int _i = 0; _i < 2; ++_i) \
;         __builtin_amdgcn_global_load_lds((const unsigned*)((const char*)(gbase) + (voff)[_i]), (PG8_LAS unsigned*)(lds + (bufoff) + ldsw + _i * 8192), 16, 0, 0); } while (0)
; #define PG8_LDA(dst, b, h) do { _Pragma("unroll") for (int m = 0; m < 4; ++m) _Pragma("unroll") for (int k = 0; k < 2; ++k) dst[m][k] = *(const PG8_LAS frag_t*)(lds + PG8_SA(b, h) + aoff + m * 2048 + k * 1024); } while (0)
; #define PG8_LDB(dst, b, h) do { _Pragma("unroll") for (int n = 0; n < 2; ++n) _Pragma("unroll") for (int k = 0; k < 2; ++k) dst[n][k] = *(const PG8_LAS frag_t*)(lds + PG8_SB(b, h) + boff + n * 2048 + k * 1024); } while (0)
; #define PG8_MMA(ai, bj, At, Bt) do { __builtin_amdgcn_s_setprio(1); _Pragma("unroll") for (int m = 0; m < 4; ++m) _Pragma("unroll") for (int n = 0; n < 2; ++n) _Pragma("unroll") for (int k = 0; k < 2; ++k) \
;         acc[ai][bj][m][n] = mma1v<MMAV>(Bt[n][k], At[m][k], acc[ai][bj][m][n]); __builtin_amdgcn_s_setprio(0); } while (0)
; #define PG8_WAIT_V(n) asm volatile("s_waitcnt vmcnt(" #n ")" ::: "memory")
; #define PG8_WAIT_L(n) asm volatile("s_waitcnt lgkmcnt(" #n ")" ::: "memory")
;     ...
;         const bool has_next = S.next(ui + 1, nxt);
;         const char* nA = has_next ? (const char*)g.A + (size_t)nxt.pm * tstep : cA; const char* nB = has_next ? (const char*)g.Bt + (size_t)nxt.pn * tstep : cB;
;         for (int t = 0; t < nt; t += 2) {
;             const bool last = (t == nt - 2);
;             const char* a1 = cA + (size_t)(t + 1) * kstep;
;             const char* a2 = last ? nA : cA + (size_t)(t + 2) * kstep; const char* b2 = last ? nB : cB + (size_t)(t + 2) * kstepB;
;             const char* a3 = a2 + kstep; const char* b3 = b2 + kstepB;
;             if (last && has_next) S.a_ready(nxt);
;             if constexpr (SP2) {
;             PG8_LDB(B0, 0, 0); PG8_LDB(B1, 0, 1); PG8_SCHED; PG8_LDA(At, 0, 0); PG8_STAGE(PG8_SA(1, 1), a1 + hstep, voffA);
;             PG8_WAIT_V(8); PG8_WAIT_L(0); PG8_BAR; PG8_MMA(0, 0, At, B0); PG8_MMA(0, 1, At, B1); PG8_BAR; PG8_SCHED;
;             PG8_LDA(At, 0, 1); PG8_STAGE(PG8_SB(0, 0), b2, voffB); PG8_STAGE(PG8_SB(0, 1), b2 + hstepB, voffB); PG8_STAGE(PG8_SA(0, 0), a2, voffA);
;             PG8_WAIT_V(8); PG8_WAIT_L(0); PG8_BAR; PG8_MMA(1, 0, At, B0); PG8_MMA(1, 1, At, B1); PG8_BAR; PG8_SCHED;
.LBB0_1223:
	s_add_u32 s6, s20, 0xc000
	s_addc_u32 s7, s21, 0
	s_add_u32 s49, s18, 0x10000
	s_addc_u32 s50, s19, 0
	s_mov_b32 s51, -2
	s_waitcnt lgkmcnt(0)
	s_add_u32 s18, s6, 0x4000
	s_addc_u32 s19, s7, 0
	s_cmpk_eq_i32 s51, 0x54
	s_cselect_b32 s22, s14, s18
	s_cselect_b32 s23, s15, s19
	s_cselect_b32 s20, s16, s49
	s_cselect_b32 s21, s17, s50
	s_add_u32 s18, s22, 0x8000
	s_addc_u32 s19, s23, 0
	s_add_i32 s52, 0, 0x10000
	v_add_u32_e32 v148, s52, v151
	s_add_i32 s54, 0, 0x14000
	ds_read_b128 v[130:133], v148
	ds_read_b128 v[134:137], v148 offset:1024
	ds_read_b128 v[154:157], v148 offset:2048
	ds_read_b128 v[158:161], v148 offset:3072
	v_add_u32_e32 v148, s54, v151
	ds_read_b128 v[174:177], v148
	ds_read_b128 v[178:181], v148 offset:1024
	ds_read_b128 v[182:185], v148 offset:2048
	ds_read_b128 v[186:189], v148 offset:3072
	v_lshl_add_u64 v[148:149], s[6:7], 0, v[144:145]
	s_add_i32 m0, s31, 0xc000
	ds_read_b128 v[216:219], v152
	ds_read_b128 v[220:223], v152 offset:1024
	ds_read_b128 v[224:227], v152 offset:2048
	ds_read_b128 v[228:231], v152 offset:3072
	ds_read_b128 v[232:235], v152 offset:4096
	ds_read_b128 v[236:239], v152 offset:5120
	ds_read_b128 v[240:243], v152 offset:6144
	ds_read_b128 v[244:247], v152 offset:7168
	global_load_lds_dwordx4 v[148:149], off
	v_lshl_add_u64 v[148:149], s[6:7], 0, v[146:147]
	s_add_i32 m0, s31, 0xe000
	s_nop 0
	global_load_lds_dwordx4 v[148:149], off
	s_waitcnt vmcnt(8)
	s_waitcnt lgkmcnt(0)
	s_barrier
	s_setprio 1
	s_waitcnt lgkmcnt(0)
	v_mfma_f32_16x16x32_bf16 v[126:129], v[130:133], v[216:219], 0
	v_mfma_f32_16x16x32_bf16 v[122:125], v[154:157], v[216:219], 0
	v_mfma_f32_16x16x32_bf16 v[110:113], v[130:133], v[224:227], 0
	v_mfma_f32_16x16x32_bf16 v[106:109], v[154:157], v[224:227], 0
	v_mfma_f32_16x16x32_bf16 v[94:97], v[130:133], v[232:235], 0
	v_mfma_f32_16x16x32_bf16 v[90:93], v[154:157], v[232:235], 0
	v_mfma_f32_16x16x32_bf16 v[78:81], v[130:133], v[240:243], 0
	v_mfma_f32_16x16x32_bf16 v[74:77], v[154:157], v[240:243], 0
	v_mfma_f32_16x16x32_bf16 v[126:129], v[134:137], v[220:223], v[126:129]
	v_mfma_f32_16x16x32_bf16 v[122:125], v[158:161], v[220:223], v[122:125]
	v_mfma_f32_16x16x32_bf16 v[110:113], v[134:137], v[228:231], v[110:113]
	v_mfma_f32_16x16x32_bf16 v[106:109], v[158:161], v[228:231], v[106:109]
	v_mfma_f32_16x16x32_bf16 v[94:97], v[134:137], v[236:239], v[94:97]
	v_mfma_f32_16x16x32_bf16 v[90:93], v[158:161], v[236:239], v[90:93]
	v_mfma_f32_16x16x32_bf16 v[78:81], v[134:137], v[244:247], v[78:81]
	v_mfma_f32_16x16x32_bf16 v[74:77], v[158:161], v[244:247], v[74:77]
	s_setprio 0
	s_setprio 1
	v_mfma_f32_16x16x32_bf16 v[118:121], v[174:177], v[216:219], 0
	v_mfma_f32_16x16x32_bf16 v[114:117], v[182:185], v[216:219], 0
	v_mfma_f32_16x16x32_bf16 v[102:105], v[174:177], v[224:227], 0
	v_mfma_f32_16x16x32_bf16 v[98:101], v[182:185], v[224:227], 0
	v_mfma_f32_16x16x32_bf16 v[86:89], v[174:177], v[232:235], 0
	v_mfma_f32_16x16x32_bf16 v[82:85], v[182:185], v[232:235], 0
	v_mfma_f32_16x16x32_bf16 v[70:73], v[174:177], v[240:243], 0
	v_mfma_f32_16x16x32_bf16 v[66:69], v[182:185], v[240:243], 0
	v_mfma_f32_16x16x32_bf16 v[118:121], v[178:181], v[220:223], v[118:121]
	v_mfma_f32_16x16x32_bf16 v[114:117], v[186:189], v[220:223], v[114:117]
	v_mfma_f32_16x16x32_bf16 v[102:105], v[178:181], v[228:231], v[102:105]
	v_mfma_f32_16x16x32_bf16 v[98:101], v[186:189], v[228:231], v[98:101]
	v_mfma_f32_16x16x32_bf16 v[86:89], v[178:181], v[236:239], v[86:89]
	v_mfma_f32_16x16x32_bf16 v[82:85], v[186:189], v[236:239], v[82:85]
	v_mfma_f32_16x16x32_bf16 v[70:73], v[178:181], v[244:247], v[70:73]
	v_mfma_f32_16x16x32_bf16 v[66:69], v[186:189], v[244:247], v[66:69]
	s_setprio 0
	s_barrier
	s_add_i32 s52, s52, s30
	v_lshl_add_u64 v[148:149], s[20:21], 0, v[162:163]
	s_mov_b32 m0, s52
	ds_read_b128 v[216:219], v152 offset:16384
	ds_read_b128 v[220:223], v152 offset:17408
	ds_read_b128 v[224:227], v152 offset:18432
	ds_read_b128 v[228:231], v152 offset:19456
	ds_read_b128 v[232:235], v152 offset:20480
	ds_read_b128 v[236:239], v152 offset:21504
	ds_read_b128 v[240:243], v152 offset:22528
	ds_read_b128 v[244:247], v152 offset:23552
	global_load_lds_dwordx4 v[148:149], off
	s_add_i32 m0, s52, 0x2000
	s_add_u32 s52, s20, 0x4000
	v_lshl_add_u64 v[148:149], s[20:21], 0, v[142:143]
	s_addc_u32 s53, s21, 0
	s_add_i32 s54, s54, s30
	global_load_lds_dwordx4 v[148:149], off
	v_lshl_add_u64 v[148:149], s[52:53], 0, v[162:163]
	s_mov_b32 m0, s54
	s_nop 0
	global_load_lds_dwordx4 v[148:149], off
	v_lshl_add_u64 v[148:149], s[52:53], 0, v[142:143]
	s_add_i32 m0, s54, 0x2000
	s_nop 0
	global_load_lds_dwordx4 v[148:149], off
	v_lshl_add_u64 v[148:149], s[22:23], 0, v[138:139]
	s_mov_b32 m0, s31
	s_nop 0
	global_load_lds_dwordx4 v[148:149], off
	v_lshl_add_u64 v[148:149], s[22:23], 0, v[140:141]
	s_mov_b32 m0, s34
	s_nop 0
	global_load_lds_dwordx4 v[148:149], off
	s_waitcnt vmcnt(8)
	s_waitcnt lgkmcnt(0)
	s_barrier
; #define PG8_STAGE(bufoff, gbase, voff) do { _Pragma("unroll") for (int _i = 0; _i < 2; ++_i) \
;         __builtin_amdgcn_global_load_lds((const unsigned*)((const char*)(gbase) + (voff)[_i]), (PG8_LAS unsigned*)(lds + (bufoff) + ldsw + _i * 8192), 16, 0, 0); } while (0)
; #define PG8_LDA(dst, b, h) do { _Pragma("unroll") for (int m = 0; m < 4; ++m) _Pragma("unroll") for (int k = 0; k < 2; ++k) dst[m][k] = *(const PG8_LAS frag_t*)(lds + PG8_SA(b, h) + aoff + m * 2048 + k * 1024); } while (0)
; #define PG8_LDB(dst, b, h) do { _Pragma("unroll") for (int n = 0; n < 2; ++n) _Pragma("unroll") for (int k = 0; k < 2; ++k) dst[n][k] = *(const PG8_LAS frag_t*)(lds + PG8_SB(b, h) + boff + n * 2048 + k * 1024); } while (0)
; #define PG8_MMA(ai, bj, At, Bt) do { __builtin_amdgcn_s_setprio(1); _Pragma("unroll") for (int m = 0; m < 4; ++m) _Pragma("unroll") for (int n = 0; n < 2; ++n) _Pragma("unroll") for (int k = 0; k < 2; ++k) \
;         acc[ai][bj][m][n] = mma1v<MMAV>(Bt[n][k], At[m][k], acc[ai][bj][m][n]); __builtin_amdgcn_s_setprio(0); } while (0)
; #define PG8_WAIT_V(n) asm volatile("s_waitcnt vmcnt(" #n ")" ::: "memory")
; #define PG8_WAIT_L(n) asm volatile("s_waitcnt lgkmcnt(" #n ")" ::: "memory")
; #define PG8_BAR __builtin_amdgcn_s_barrier()
; #define PG8_SCHED __builtin_amdgcn_sched_barrier(0)
;     ...
;             PG8_WAIT_V(8); PG8_WAIT_L(0); PG8_BAR; PG8_MMA(0, 0, At, B0); PG8_MMA(0, 1, At, B1); PG8_BAR; PG8_SCHED;
;             PG8_LDA(At, 0, 1); PG8_STAGE(PG8_SB(0, 0), b2, voffB); PG8_STAGE(PG8_SB(0, 1), b2 + hstepB, voffB); PG8_STAGE(PG8_SA(0, 0), a2, voffA);
;             PG8_WAIT_V(8); PG8_WAIT_L(0); PG8_BAR; PG8_MMA(1, 0, At, B0); PG8_MMA(1, 1, At, B1); PG8_BAR; PG8_SCHED;
;             PG8_LDB(B0, 1, 0); PG8_LDB(B1, 1, 1); PG8_SCHED; PG8_LDA(At, 1, 0); PG8_STAGE(PG8_SA(0, 1), a2 + hstep, voffA);
;             PG8_WAIT_V(8); PG8_WAIT_L(0); PG8_BAR; PG8_MMA(0, 0, At, B0); PG8_MMA(0, 1, At, B1); PG8_BAR; PG8_SCHED;
	s_setprio 1
	s_waitcnt lgkmcnt(0)
	v_mfma_f32_16x16x32_bf16 v[62:65], v[130:133], v[216:219], 0
	v_mfma_f32_16x16x32_bf16 v[58:61], v[154:157], v[216:219], 0
	v_mfma_f32_16x16x32_bf16 v[46:49], v[130:133], v[224:227], 0
	v_mfma_f32_16x16x32_bf16 v[42:45], v[154:157], v[224:227], 0
	v_mfma_f32_16x16x32_bf16 v[30:33], v[130:133], v[232:235], 0
	v_mfma_f32_16x16x32_bf16 v[26:29], v[154:157], v[232:235], 0
	v_mfma_f32_16x16x32_bf16 v[14:17], v[130:133], v[240:243], 0
	v_mfma_f32_16x16x32_bf16 v[10:13], v[154:157], v[240:243], 0
	v_mfma_f32_16x16x32_bf16 v[62:65], v[134:137], v[220:223], v[62:65]
	v_mfma_f32_16x16x32_bf16 v[58:61], v[158:161], v[220:223], v[58:61]
	v_mfma_f32_16x16x32_bf16 v[46:49], v[134:137], v[228:231], v[46:49]
	v_mfma_f32_16x16x32_bf16 v[42:45], v[158:161], v[228:231], v[42:45]
	v_mfma_f32_16x16x32_bf16 v[30:33], v[134:137], v[236:239], v[30:33]
	v_mfma_f32_16x16x32_bf16 v[26:29], v[158:161], v[236:239], v[26:29]
	v_mfma_f32_16x16x32_bf16 v[14:17], v[134:137], v[244:247], v[14:17]
	v_mfma_f32_16x16x32_bf16 v[10:13], v[158:161], v[244:247], v[10:13]
	s_setprio 0
	s_setprio 1
	v_mfma_f32_16x16x32_bf16 v[54:57], v[174:177], v[216:219], 0
	v_mfma_f32_16x16x32_bf16 v[50:53], v[182:185], v[216:219], 0
	v_mfma_f32_16x16x32_bf16 v[38:41], v[174:177], v[224:227], 0
	v_mfma_f32_16x16x32_bf16 v[34:37], v[182:185], v[224:227], 0
	v_mfma_f32_16x16x32_bf16 v[22:25], v[174:177], v[232:235], 0
	v_mfma_f32_16x16x32_bf16 v[18:21], v[182:185], v[232:235], 0
	v_mfma_f32_16x16x32_bf16 v[6:9], v[174:177], v[240:243], 0
	v_mfma_f32_16x16x32_bf16 v[2:5], v[182:185], v[240:243], 0
	v_mfma_f32_16x16x32_bf16 v[54:57], v[178:181], v[220:223], v[54:57]
	v_mfma_f32_16x16x32_bf16 v[50:53], v[186:189], v[220:223], v[50:53]
	v_mfma_f32_16x16x32_bf16 v[38:41], v[178:181], v[228:231], v[38:41]
	v_mfma_f32_16x16x32_bf16 v[34:37], v[186:189], v[228:231], v[34:37]
	v_mfma_f32_16x16x32_bf16 v[22:25], v[178:181], v[236:239], v[22:25]
	v_mfma_f32_16x16x32_bf16 v[18:21], v[186:189], v[236:239], v[18:21]
	v_mfma_f32_16x16x32_bf16 v[6:9], v[178:181], v[244:247], v[6:9]
	v_mfma_f32_16x16x32_bf16 v[2:5], v[186:189], v[244:247], v[2:5]
	s_setprio 0
	s_barrier
	s_add_i32 s52, 0, 0x18000
	v_add_u32_e32 v148, s52, v151
	s_add_i32 s53, 0, 0x1c000
	ds_read_b128 v[130:133], v148
	ds_read_b128 v[134:137], v148 offset:1024
	ds_read_b128 v[154:157], v148 offset:2048
	ds_read_b128 v[158:161], v148 offset:3072
	v_add_u32_e32 v148, s53, v151
	ds_read_b128 v[174:177], v148
	ds_read_b128 v[178:181], v148 offset:1024
	ds_read_b128 v[182:185], v148 offset:2048
	ds_read_b128 v[186:189], v148 offset:3072
	s_add_u32 s22, s22, 0x4000
	s_addc_u32 s23, s23, 0
	s_mov_b32 m0, s35
	v_lshl_add_u64 v[148:149], s[22:23], 0, v[138:139]
	ds_read_b128 v[216:219], v152 offset:32768
	ds_read_b128 v[220:223], v152 offset:33792
	ds_read_b128 v[224:227], v152 offset:34816
	ds_read_b128 v[228:231], v152 offset:35840
	ds_read_b128 v[232:235], v152 offset:36864
	ds_read_b128 v[236:239], v152 offset:37888
	ds_read_b128 v[240:243], v152 offset:38912
	ds_read_b128 v[244:247], v152 offset:39936
	global_load_lds_dwordx4 v[148:149], off
	v_lshl_add_u64 v[148:149], s[22:23], 0, v[140:141]
	s_mov_b32 m0, s36
	s_nop 0
	global_load_lds_dwordx4 v[148:149], off
	s_waitcnt vmcnt(8)
	s_waitcnt lgkmcnt(0)
	s_barrier
	s_setprio 1
	s_waitcnt lgkmcnt(0)
	v_mfma_f32_16x16x32_bf16 v[126:129], v[130:133], v[216:219], v[126:129]
	v_mfma_f32_16x16x32_bf16 v[122:125], v[154:157], v[216:219], v[122:125]
	v_mfma_f32_16x16x32_bf16 v[110:113], v[130:133], v[224:227], v[110:113]
	v_mfma_f32_16x16x32_bf16 v[106:109], v[154:157], v[224:227], v[106:109]
	v_mfma_f32_16x16x32_bf16 v[94:97], v[130:133], v[232:235], v[94:97]
	v_mfma_f32_16x16x32_bf16 v[90:93], v[154:157], v[232:235], v[90:93]
	v_mfma_f32_16x16x32_bf16 v[78:81], v[130:133], v[240:243], v[78:81]
	v_mfma_f32_16x16x32_bf16 v[74:77], v[154:157], v[240:243], v[74:77]
	v_mfma_f32_16x16x32_bf16 v[126:129], v[134:137], v[220:223], v[126:129]
	v_mfma_f32_16x16x32_bf16 v[122:125], v[158:161], v[220:223], v[122:125]
	v_mfma_f32_16x16x32_bf16 v[110:113], v[134:137], v[228:231], v[110:113]
	v_mfma_f32_16x16x32_bf16 v[106:109], v[158:161], v[228:231], v[106:109]
	v_mfma_f32_16x16x32_bf16 v[94:97], v[134:137], v[236:239], v[94:97]
	v_mfma_f32_16x16x32_bf16 v[90:93], v[158:161], v[236:239], v[90:93]
	v_mfma_f32_16x16x32_bf16 v[78:81], v[134:137], v[244:247], v[78:81]
	v_mfma_f32_16x16x32_bf16 v[74:77], v[158:161], v[244:247], v[74:77]
	s_setprio 0
	s_setprio 1
	v_mfma_f32_16x16x32_bf16 v[118:121], v[174:177], v[216:219], v[118:121]
	v_mfma_f32_16x16x32_bf16 v[114:117], v[182:185], v[216:219], v[114:117]
	v_mfma_f32_16x16x32_bf16 v[102:105], v[174:177], v[224:227], v[102:105]
	v_mfma_f32_16x16x32_bf16 v[98:101], v[182:185], v[224:227], v[98:101]
	v_mfma_f32_16x16x32_bf16 v[86:89], v[174:177], v[232:235], v[86:89]
	v_mfma_f32_16x16x32_bf16 v[82:85], v[182:185], v[232:235], v[82:85]
	v_mfma_f32_16x16x32_bf16 v[70:73], v[174:177], v[240:243], v[70:73]
	v_mfma_f32_16x16x32_bf16 v[66:69], v[182:185], v[240:243], v[66:69]
	v_mfma_f32_16x16x32_bf16 v[118:121], v[178:181], v[220:223], v[118:121]
	v_mfma_f32_16x16x32_bf16 v[114:117], v[186:189], v[220:223], v[114:117]
	v_mfma_f32_16x16x32_bf16 v[102:105], v[178:181], v[228:231], v[102:105]
	v_mfma_f32_16x16x32_bf16 v[98:101], v[186:189], v[228:231], v[98:101]
	v_mfma_f32_16x16x32_bf16 v[86:89], v[178:181], v[236:239], v[86:89]
	v_mfma_f32_16x16x32_bf16 v[82:85], v[186:189], v[236:239], v[82:85]
	v_mfma_f32_16x16x32_bf16 v[70:73], v[178:181], v[244:247], v[70:73]
	v_mfma_f32_16x16x32_bf16 v[66:69], v[186:189], v[244:247], v[66:69]
	s_setprio 0
	s_barrier
; #define PG8_STAGE(bufoff, gbase, voff) do { _Pragma("unroll") for (int _i = 0; _i < 2; ++_i) \
;         __builtin_amdgcn_global_load_lds((const unsigned*)((const char*)(gbase) + (voff)[_i]), (PG8_LAS unsigned*)(lds + (bufoff) + ldsw + _i * 8192), 16, 0, 0); } while (0)
; #define PG8_LDA(dst, b, h) do { _Pragma("unroll") for (int m = 0; m < 4; ++m) _Pragma("unroll") for (int k = 0; k < 2; ++k) dst[m][k] = *(const PG8_LAS frag_t*)(lds + PG8_SA(b, h) + aoff + m * 2048 + k * 1024); } while (0)
; #define PG8_LDB(dst, b, h) do { _Pragma("unroll") for (int n = 0; n < 2; ++n) _Pragma("unroll") for (int k = 0; k < 2; ++k) dst[n][k] = *(const PG8_LAS frag_t*)(lds + PG8_SB(b, h) + boff + n * 2048 + k * 1024); } while (0)
; #define PG8_MMA(ai, bj, At, Bt) do { __builtin_amdgcn_s_setprio(1); _Pragma("unroll") for (int m = 0; m < 4; ++m) _Pragma("unroll") for (int n = 0; n < 2; ++n) _Pragma("unroll") for (int k = 0; k < 2; ++k) \
;         acc[ai][bj][m][n] = mma1v<MMAV>(Bt[n][k], At[m][k], acc[ai][bj][m][n]); __builtin_amdgcn_s_setprio(0); } while (0)
; #define PG8_WAIT_V(n) asm volatile("s_waitcnt vmcnt(" #n ")" ::: "memory")
; #define PG8_WAIT_L(n) asm volatile("s_waitcnt lgkmcnt(" #n ")" ::: "memory")
; #define PG8_BAR __builtin_amdgcn_s_barrier()
; #define PG8_SCHED __builtin_amdgcn_sched_barrier(0)
;     ...
;             PG8_LDB(B0, 1, 0); PG8_LDB(B1, 1, 1); PG8_SCHED; PG8_LDA(At, 1, 0); PG8_STAGE(PG8_SA(0, 1), a2 + hstep, voffA);
;             PG8_WAIT_V(8); PG8_WAIT_L(0); PG8_BAR; PG8_MMA(0, 0, At, B0); PG8_MMA(0, 1, At, B1); PG8_BAR; PG8_SCHED;
;             PG8_LDA(At, 1, 1); PG8_STAGE(PG8_SB(1, 0), b3, voffB); PG8_STAGE(PG8_SB(1, 1), b3 + hstepB, voffB); PG8_STAGE(PG8_SA(1, 0), a3, voffA);
;             PG8_WAIT_V(8); PG8_WAIT_L(0); PG8_BAR; PG8_MMA(1, 0, At, B0); PG8_MMA(1, 1, At, B1); PG8_BAR; PG8_SCHED;
	s_add_u32 s22, s20, 0x8000
	s_addc_u32 s23, s21, 0
	s_add_i32 s52, s52, s30
	v_lshl_add_u64 v[148:149], s[22:23], 0, v[162:163]
	s_mov_b32 m0, s52
	ds_read_b128 v[216:219], v152 offset:49152
	ds_read_b128 v[220:223], v152 offset:50176
	ds_read_b128 v[224:227], v152 offset:51200
	ds_read_b128 v[228:231], v152 offset:52224
	ds_read_b128 v[232:235], v152 offset:53248
	ds_read_b128 v[236:239], v152 offset:54272
	ds_read_b128 v[240:243], v152 offset:55296
	ds_read_b128 v[244:247], v152 offset:56320
	global_load_lds_dwordx4 v[148:149], off
	s_add_i32 m0, s52, 0x2000
	s_add_u32 s20, s20, 0xc000
	v_lshl_add_u64 v[148:149], s[22:23], 0, v[142:143]
	s_addc_u32 s21, s21, 0
	s_add_i32 s22, s53, s30
	global_load_lds_dwordx4 v[148:149], off
	v_lshl_add_u64 v[148:149], s[20:21], 0, v[162:163]
	s_mov_b32 m0, s22
	s_nop 0
	global_load_lds_dwordx4 v[148:149], off
	v_lshl_add_u64 v[148:149], s[20:21], 0, v[142:143]
	s_add_i32 m0, s22, 0x2000
	s_nop 0
	global_load_lds_dwordx4 v[148:149], off
	v_lshl_add_u64 v[148:149], s[18:19], 0, v[138:139]
	s_mov_b32 m0, s40
	s_nop 0
	global_load_lds_dwordx4 v[148:149], off
	v_lshl_add_u64 v[148:149], s[18:19], 0, v[140:141]
	s_mov_b32 m0, s41
	s_nop 0
	global_load_lds_dwordx4 v[148:149], off
	s_waitcnt vmcnt(8)
	s_waitcnt lgkmcnt(0)
	s_barrier
	s_setprio 1
	s_waitcnt lgkmcnt(0)
	v_mfma_f32_16x16x32_bf16 v[62:65], v[130:133], v[216:219], v[62:65]
	v_mfma_f32_16x16x32_bf16 v[58:61], v[154:157], v[216:219], v[58:61]
	v_mfma_f32_16x16x32_bf16 v[46:49], v[130:133], v[224:227], v[46:49]
	v_mfma_f32_16x16x32_bf16 v[42:45], v[154:157], v[224:227], v[42:45]
	v_mfma_f32_16x16x32_bf16 v[30:33], v[130:133], v[232:235], v[30:33]
	v_mfma_f32_16x16x32_bf16 v[26:29], v[154:157], v[232:235], v[26:29]
	v_mfma_f32_16x16x32_bf16 v[14:17], v[130:133], v[240:243], v[14:17]
	v_mfma_f32_16x16x32_bf16 v[10:13], v[154:157], v[240:243], v[10:13]
	v_mfma_f32_16x16x32_bf16 v[62:65], v[134:137], v[220:223], v[62:65]
	v_mfma_f32_16x16x32_bf16 v[58:61], v[158:161], v[220:223], v[58:61]
	v_mfma_f32_16x16x32_bf16 v[46:49], v[134:137], v[228:231], v[46:49]
	v_mfma_f32_16x16x32_bf16 v[42:45], v[158:161], v[228:231], v[42:45]
	v_mfma_f32_16x16x32_bf16 v[30:33], v[134:137], v[236:239], v[30:33]
	v_mfma_f32_16x16x32_bf16 v[26:29], v[158:161], v[236:239], v[26:29]
	v_mfma_f32_16x16x32_bf16 v[14:17], v[134:137], v[244:247], v[14:17]
	v_mfma_f32_16x16x32_bf16 v[10:13], v[158:161], v[244:247], v[10:13]
	s_setprio 0
	s_setprio 1
	v_mfma_f32_16x16x32_bf16 v[54:57], v[174:177], v[216:219], v[54:57]
	v_mfma_f32_16x16x32_bf16 v[50:53], v[182:185], v[216:219], v[50:53]
	v_mfma_f32_16x16x32_bf16 v[38:41], v[174:177], v[224:227], v[38:41]
	v_mfma_f32_16x16x32_bf16 v[34:37], v[182:185], v[224:227], v[34:37]
	v_mfma_f32_16x16x32_bf16 v[22:25], v[174:177], v[232:235], v[22:25]
	v_mfma_f32_16x16x32_bf16 v[18:21], v[182:185], v[232:235], v[18:21]
	v_mfma_f32_16x16x32_bf16 v[6:9], v[174:177], v[240:243], v[6:9]
	v_mfma_f32_16x16x32_bf16 v[2:5], v[182:185], v[240:243], v[2:5]
	v_mfma_f32_16x16x32_bf16 v[54:57], v[178:181], v[220:223], v[54:57]
	v_mfma_f32_16x16x32_bf16 v[50:53], v[186:189], v[220:223], v[50:53]
	v_mfma_f32_16x16x32_bf16 v[38:41], v[178:181], v[228:231], v[38:41]
	v_mfma_f32_16x16x32_bf16 v[34:37], v[186:189], v[228:231], v[34:37]
	v_mfma_f32_16x16x32_bf16 v[22:25], v[178:181], v[236:239], v[22:25]
	v_mfma_f32_16x16x32_bf16 v[18:21], v[186:189], v[236:239], v[18:21]
	v_mfma_f32_16x16x32_bf16 v[6:9], v[178:181], v[244:247], v[6:9]
	v_mfma_f32_16x16x32_bf16 v[2:5], v[186:189], v[244:247], v[2:5]
	s_setprio 0
	s_barrier
	s_add_i32 s51, s51, 2
	s_add_u32 s6, s6, 0x10000
	s_addc_u32 s7, s7, 0
	s_add_u32 s49, s49, 0x10000
	s_addc_u32 s50, s50, 0
